# non-temporal hints on read-once / write-once streams: x (f32) loads in prep and LayerNorm 1, f32 weight loads of the transposes, final f32 output stores
# speedup vs baseline: 1.0105x; 1.0055x over previous
; __device__ __forceinline__ float bflo(unsigned u) { return __uint_as_float(u << 16); }
; __device__ __forceinline__ float bfhi(unsigned u) { return __uint_as_float(u & 0xffff0000u); }
; __device__ void ln_phase2(const bf16_t* __restrict__ mix, const float* __restrict__ Rf, const bf16_t* __restrict__ Rb, const float* __restrict__ gam, const float* __restrict__ bet, bf16_t* ob, float* of) {
;     ...
;     for (int row = blockIdx.x * 8 + wid; row < T_TOK; row += gridDim.x * 8) {
;         const size_t ro = (size_t)row * DM + lane * 8;
;         float v[32]; float s = 0.f;
; #pragma unroll
;         for (int j = 0; j < 4; ++j) {
;             const u32x4 m = *(const u32x4*)(mix + ro + 512 * j);
;             float r[8];
;             if (Rf) { const f32x4 a = *(const f32x4*)(Rf + ro + 512 * j), b = *(const f32x4*)(Rf + ro + 512 * j + 4);
;                 r[0] = a[0]; r[1] = a[1]; r[2] = a[2]; r[3] = a[3]; r[4] = b[0]; r[5] = b[1]; r[6] = b[2]; r[7] = b[3]; }
;             else { const u32x4 rb = *(const u32x4*)(Rb + ro + 512 * j);
;                 r[0] = bflo(rb.x); r[1] = bfhi(rb.x); r[2] = bflo(rb.y); r[3] = bfhi(rb.y); r[4] = bflo(rb.z); r[5] = bfhi(rb.z); r[6] = bflo(rb.w); r[7] = bfhi(rb.w); }
;             v[8 * j + 0] = DN_ALPHA * r[0] + bflo(m.x); v[8 * j + 1] = DN_ALPHA * r[1] + bfhi(m.x); v[8 * j + 2] = DN_ALPHA * r[2] + bflo(m.y); v[8 * j + 3] = DN_ALPHA * r[3] + bfhi(m.y);
;             v[8 * j + 4] = DN_ALPHA * r[4] + bflo(m.z); v[8 * j + 5] = DN_ALPHA * r[5] + bfhi(m.z); v[8 * j + 6] = DN_ALPHA * r[6] + bflo(m.w); v[8 * j + 7] = DN_ALPHA * r[7] + bfhi(m.w);
; #pragma unroll
;             for (int e = 0; e < 8; ++e) s += v[8 * j + e];
;         }
; #pragma unroll
;         for (int o = 32; o; o >>= 1) s += __shfl_xor(s, o);
;         const float mean = s * (1.0f / 2048.0f);
;         float q = 0.f;
; #pragma unroll
;         for (int e = 0; e < 32; ++e) { const float dlt = v[e] - mean; q += dlt * dlt; }
; #pragma unroll
;         for (int o = 32; o; o >>= 1) q += __shfl_xor(q, o);
;         const float rstd = rsqrtf(q * (1.0f / 2048.0f) + 1e-5f);
.LBB0_31:
	v_ashrrev_i32_e32 v1, 31, v0
	v_lshlrev_b64 v[88:89], 11, v[0:1]
	v_or_b32_e32 v88, v88, v84
	v_lshlrev_b64 v[68:69], 1, v[88:89]
	v_lshl_add_u64 v[70:71], s[68:69], 0, v[68:69]
	v_lshl_add_u64 v[72:73], s[92:93], 0, v[68:69]
	global_load_dwordx4 v[94:97], v[70:71], off
	global_load_dwordx4 v[98:101], v[72:73], off
	global_load_dwordx4 v[110:113], v[70:71], off offset:1024
	global_load_dwordx4 v[114:117], v[72:73], off offset:1024
	global_load_dwordx4 v[76:79], v[70:71], off offset:2048
	global_load_dwordx4 v[80:83], v[72:73], off offset:2048
	s_nop 0
	global_load_dwordx4 v[68:71], v[70:71], off offset:3072
	s_nop 0
	global_load_dwordx4 v[72:75], v[72:73], off offset:3072
	v_add_u32_e32 v0, s10, v0
	s_waitcnt vmcnt(0)
	v_lshlrev_b32_e32 v92, 16, v97
	v_and_b32_e32 v93, 0xffff0000, v97
	v_and_b32_e32 v97, 0xffff0000, v94
	s_waitcnt vmcnt(5)
	v_lshlrev_b32_e32 v102, 16, v110
	v_and_b32_e32 v103, 0xffff0000, v110
	v_lshlrev_b32_e32 v104, 16, v111
	s_waitcnt vmcnt(1)
	v_and_b32_e32 v90, 0xffff0000, v70
	s_waitcnt vmcnt(0)
	v_and_b32_e32 v86, 0xffff0000, v74
	v_lshlrev_b32_e32 v87, 16, v74
	v_lshlrev_b32_e32 v91, 16, v70
	v_and_b32_e32 v74, 0xffff0000, v75
	v_lshlrev_b32_e32 v75, 16, v75
	v_and_b32_e32 v70, 0xffff0000, v71
	v_lshlrev_b32_e32 v71, 16, v71
	v_pk_fma_f32 v[86:87], v[86:87], s[4:5], v[90:91] op_sel_hi:[1,0,1]
	v_pk_fma_f32 v[74:75], v[74:75], s[4:5], v[70:71] op_sel_hi:[1,0,1]
	v_lshl_add_u64 v[70:71], v[88:89], 2, s[90:91]
	v_lshlrev_b32_e32 v88, 16, v100
	v_and_b32_e32 v89, 0xffff0000, v100
	v_lshlrev_b32_e32 v90, 16, v96
	v_and_b32_e32 v91, 0xffff0000, v96
	v_pk_fma_f32 v[88:89], v[88:89], s[4:5], v[90:91] op_sel_hi:[1,0,1]
	v_lshlrev_b32_e32 v90, 16, v101
	v_and_b32_e32 v91, 0xffff0000, v101
	v_pk_fma_f32 v[90:91], v[90:91], s[4:5], v[92:93] op_sel_hi:[1,0,1]
	v_lshlrev_b32_e32 v92, 16, v98
	v_and_b32_e32 v93, 0xffff0000, v98
	v_lshlrev_b32_e32 v96, 16, v94
	v_pk_fma_f32 v[92:93], v[92:93], s[4:5], v[96:97] op_sel_hi:[1,0,1]
	v_lshlrev_b32_e32 v96, 16, v99
	v_add_f32_e32 v1, 0, v92
	v_and_b32_e32 v97, 0xffff0000, v99
	v_lshlrev_b32_e32 v94, 16, v95
	v_and_b32_e32 v95, 0xffff0000, v95
	v_add_f32_e32 v1, v93, v1
	v_pk_fma_f32 v[94:95], v[96:97], s[4:5], v[94:95] op_sel_hi:[1,0,1]
	v_lshlrev_b32_e32 v96, 16, v116
	v_add_f32_e32 v1, v94, v1
	v_add_f32_e32 v1, v95, v1
	v_add_f32_e32 v1, v88, v1
	v_and_b32_e32 v97, 0xffff0000, v116
	v_lshlrev_b32_e32 v98, 16, v112
	v_and_b32_e32 v99, 0xffff0000, v112
	v_add_f32_e32 v1, v89, v1
	v_pk_fma_f32 v[96:97], v[96:97], s[4:5], v[98:99] op_sel_hi:[1,0,1]
	v_lshlrev_b32_e32 v98, 16, v117
	v_and_b32_e32 v99, 0xffff0000, v117
	v_lshlrev_b32_e32 v100, 16, v113
	v_and_b32_e32 v101, 0xffff0000, v113
	v_add_f32_e32 v1, v90, v1
	v_pk_fma_f32 v[98:99], v[98:99], s[4:5], v[100:101] op_sel_hi:[1,0,1]
	v_lshlrev_b32_e32 v100, 16, v114
	v_and_b32_e32 v101, 0xffff0000, v114
	v_add_f32_e32 v1, v91, v1
	v_pk_fma_f32 v[102:103], v[100:101], s[4:5], v[102:103] op_sel_hi:[1,0,1]
	v_lshlrev_b32_e32 v100, 16, v115
	v_add_f32_e32 v1, v102, v1
	v_and_b32_e32 v101, 0xffff0000, v115
	v_and_b32_e32 v105, 0xffff0000, v111
	v_add_f32_e32 v1, v103, v1
	v_pk_fma_f32 v[104:105], v[100:101], s[4:5], v[104:105] op_sel_hi:[1,0,1]
	v_lshlrev_b32_e32 v100, 16, v82
	v_add_f32_e32 v1, v104, v1
	v_add_f32_e32 v1, v105, v1
	v_add_f32_e32 v1, v96, v1
	v_add_f32_e32 v1, v97, v1
	v_and_b32_e32 v101, 0xffff0000, v82
	v_lshlrev_b32_e32 v110, 16, v78
	v_and_b32_e32 v111, 0xffff0000, v78
	v_lshlrev_b32_e32 v82, 16, v83
	v_and_b32_e32 v83, 0xffff0000, v83
	v_lshlrev_b32_e32 v78, 16, v79
	v_and_b32_e32 v79, 0xffff0000, v79
	v_add_f32_e32 v1, v98, v1
	v_pk_fma_f32 v[100:101], v[100:101], s[4:5], v[110:111] op_sel_hi:[1,0,1]
	v_pk_fma_f32 v[78:79], v[82:83], s[4:5], v[78:79] op_sel_hi:[1,0,1]
	v_lshlrev_b32_e32 v82, 16, v80
	v_and_b32_e32 v83, 0xffff0000, v80
	v_lshlrev_b32_e32 v110, 16, v76
	v_and_b32_e32 v111, 0xffff0000, v76
	v_add_f32_e32 v1, v99, v1
	v_pk_fma_f32 v[82:83], v[82:83], s[4:5], v[110:111] op_sel_hi:[1,0,1]
	v_lshlrev_b32_e32 v80, 16, v81
	v_add_f32_e32 v1, v82, v1
	v_and_b32_e32 v81, 0xffff0000, v81
	v_lshlrev_b32_e32 v76, 16, v77
	v_and_b32_e32 v77, 0xffff0000, v77
	v_add_f32_e32 v1, v83, v1
	v_pk_fma_f32 v[76:77], v[80:81], s[4:5], v[76:77] op_sel_hi:[1,0,1]
	v_lshlrev_b32_e32 v80, 16, v72
	v_add_f32_e32 v1, v76, v1
	v_add_f32_e32 v1, v77, v1
	v_add_f32_e32 v1, v100, v1
	v_add_f32_e32 v1, v101, v1
	v_add_f32_e32 v1, v78, v1
	v_and_b32_e32 v81, 0xffff0000, v72
	v_lshlrev_b32_e32 v110, 16, v68
	v_and_b32_e32 v111, 0xffff0000, v68
	v_add_f32_e32 v1, v79, v1
	v_pk_fma_f32 v[80:81], v[80:81], s[4:5], v[110:111] op_sel_hi:[1,0,1]
	v_lshlrev_b32_e32 v72, 16, v73
	v_add_f32_e32 v1, v80, v1
	v_and_b32_e32 v73, 0xffff0000, v73
	v_lshlrev_b32_e32 v68, 16, v69
	v_and_b32_e32 v69, 0xffff0000, v69
	v_add_f32_e32 v1, v81, v1
	v_pk_fma_f32 v[68:69], v[72:73], s[4:5], v[68:69] op_sel_hi:[1,0,1]
	s_nop 0
	v_add_f32_e32 v1, v68, v1
	v_add_f32_e32 v1, v69, v1
	v_add_f32_e32 v1, v87, v1
	v_add_f32_e32 v1, v86, v1
	v_add_f32_e32 v1, v75, v1
	v_add_f32_e32 v1, v74, v1
	v_mov_b32_e32 v72, v1
	s_nop 1
	v_permlane32_swap_b32 v72, v1
	v_add_f32_e32 v1, v1, v72
	v_mov_b32_e32 v72, v1
	s_nop 1
	v_permlane16_swap_b32 v72, v1
	v_add_f32_e32 v1, v1, v72
	s_nop 1
	v_add_f32_dpp v1, v1, v1 quad_perm:[1,0,3,2] row_mask:0xf bank_mask:0xf
	s_nop 1
	v_add_f32_dpp v1, v1, v1 quad_perm:[2,3,0,1] row_mask:0xf bank_mask:0xf
	s_nop 1
	v_add_f32_dpp v1, v1, v1 row_half_mirror row_mask:0xf bank_mask:0xf
	s_nop 1
	v_add_f32_dpp v1, v1, v1 row_mirror row_mask:0xf bank_mask:0xf
	v_mul_f32_e32 v72, 0x3a000000, v1
	v_pk_add_f32 v[92:93], v[92:93], v[72:73] op_sel_hi:[1,0] neg_lo:[0,1] neg_hi:[0,1]
; __device__ __forceinline__ unsigned cvt_pk_bf16(float lo, float hi) { const f32x2v v = {lo, hi}; const b16x2v r = __builtin_convertvector(v, b16x2v); return __builtin_bit_cast(unsigned, r); }
; __device__ void ln_phase2(const bf16_t* __restrict__ mix, const float* __restrict__ Rf, const bf16_t* __restrict__ Rb, const float* __restrict__ gam, const float* __restrict__ bet, bf16_t* ob, float* of) {
;     ...
;         float q = 0.f;
; #pragma unroll
;         for (int e = 0; e < 32; ++e) { const float dlt = v[e] - mean; q += dlt * dlt; }
; #pragma unroll
;         for (int o = 32; o; o >>= 1) q += __shfl_xor(q, o);
;         const float rstd = rsqrtf(q * (1.0f / 2048.0f) + 1e-5f);
; #pragma unroll
;         for (int j = 0; j < 4; ++j) {
;             const f32x4 g0 = *(const f32x4*)(gam + lane * 8 + 512 * j), g1 = *(const f32x4*)(gam + lane * 8 + 512 * j + 4);
;             const f32x4 b0 = *(const f32x4*)(bet + lane * 8 + 512 * j), b1 = *(const f32x4*)(bet + lane * 8 + 512 * j + 4);
;             f32x4 y0, y1;
; #pragma unroll
;             for (int e = 0; e < 4; ++e) { y0[e] = (v[8 * j + e] - mean) * rstd * g0[e] + b0[e]; y1[e] = (v[8 * j + 4 + e] - mean) * rstd * g1[e] + b1[e]; }
;             if (ob) { u32x4 w; w.x = cvt_pk_bf16(y0[0], y0[1]); w.y = cvt_pk_bf16(y0[2], y0[3]); w.z = cvt_pk_bf16(y1[0], y1[1]); w.w = cvt_pk_bf16(y1[2], y1[3]); *(u32x4*)(ob + ro + 512 * j) = w; }
;             else { *(f32x4*)(of + ro + 512 * j) = y0; *(f32x4*)(of + ro + 512 * j + 4) = y1; }
;         }
	v_pk_add_f32 v[94:95], v[94:95], v[72:73] op_sel_hi:[1,0] neg_lo:[0,1] neg_hi:[0,1]
	v_pk_mul_f32 v[110:111], v[92:93], v[92:93]
	v_pk_mul_f32 v[112:113], v[94:95], v[94:95]
	v_add_f32_e32 v1, v110, v111
	v_pk_add_f32 v[88:89], v[88:89], v[72:73] op_sel_hi:[1,0] neg_lo:[0,1] neg_hi:[0,1]
	v_add_f32_e32 v1, v112, v1
	v_pk_mul_f32 v[114:115], v[88:89], v[88:89]
	v_add_f32_e32 v1, v113, v1
	v_pk_add_f32 v[90:91], v[90:91], v[72:73] op_sel_hi:[1,0] neg_lo:[0,1] neg_hi:[0,1]
	v_add_f32_e32 v1, v114, v1
	v_pk_mul_f32 v[116:117], v[90:91], v[90:91]
	v_add_f32_e32 v1, v115, v1
	v_pk_add_f32 v[102:103], v[102:103], v[72:73] op_sel_hi:[1,0] neg_lo:[0,1] neg_hi:[0,1]
	v_add_f32_e32 v1, v116, v1
	v_pk_mul_f32 v[118:119], v[102:103], v[102:103]
	v_add_f32_e32 v1, v117, v1
	v_pk_add_f32 v[104:105], v[104:105], v[72:73] op_sel_hi:[1,0] neg_lo:[0,1] neg_hi:[0,1]
	v_add_f32_e32 v1, v118, v1
	v_pk_mul_f32 v[120:121], v[104:105], v[104:105]
	v_add_f32_e32 v1, v119, v1
	v_pk_add_f32 v[96:97], v[96:97], v[72:73] op_sel_hi:[1,0] neg_lo:[0,1] neg_hi:[0,1]
	v_add_f32_e32 v1, v120, v1
	v_pk_mul_f32 v[122:123], v[96:97], v[96:97]
	v_add_f32_e32 v1, v121, v1
	v_pk_add_f32 v[98:99], v[98:99], v[72:73] op_sel_hi:[1,0] neg_lo:[0,1] neg_hi:[0,1]
	v_add_f32_e32 v1, v122, v1
	v_pk_mul_f32 v[124:125], v[98:99], v[98:99]
	v_add_f32_e32 v1, v123, v1
	v_pk_add_f32 v[82:83], v[82:83], v[72:73] op_sel_hi:[1,0] neg_lo:[0,1] neg_hi:[0,1]
	v_add_f32_e32 v1, v124, v1
	v_pk_mul_f32 v[126:127], v[82:83], v[82:83]
	v_add_f32_e32 v1, v125, v1
	v_pk_add_f32 v[128:129], v[76:77], v[72:73] op_sel_hi:[1,0] neg_lo:[0,1] neg_hi:[0,1]
	v_add_f32_e32 v1, v126, v1
	v_pk_mul_f32 v[76:77], v[128:129], v[128:129]
	v_add_f32_e32 v1, v127, v1
	v_pk_add_f32 v[100:101], v[100:101], v[72:73] op_sel_hi:[1,0] neg_lo:[0,1] neg_hi:[0,1]
	v_add_f32_e32 v1, v76, v1
	v_pk_mul_f32 v[130:131], v[100:101], v[100:101]
	v_add_f32_e32 v1, v77, v1
	v_pk_add_f32 v[132:133], v[78:79], v[72:73] op_sel_hi:[1,0] neg_lo:[0,1] neg_hi:[0,1]
	v_add_f32_e32 v1, v130, v1
	v_pk_mul_f32 v[78:79], v[132:133], v[132:133]
	v_add_f32_e32 v1, v131, v1
	v_pk_add_f32 v[80:81], v[80:81], v[72:73] op_sel_hi:[1,0] neg_lo:[0,1] neg_hi:[0,1]
	v_add_f32_e32 v1, v78, v1
	v_pk_mul_f32 v[134:135], v[80:81], v[80:81]
	v_add_f32_e32 v1, v79, v1
	v_pk_add_f32 v[136:137], v[68:69], v[72:73] op_sel_hi:[1,0] neg_lo:[0,1] neg_hi:[0,1]
	v_add_f32_e32 v1, v134, v1
	v_pk_mul_f32 v[68:69], v[136:137], v[136:137]
	v_add_f32_e32 v1, v135, v1
	v_pk_add_f32 v[86:87], v[86:87], v[72:73] op_sel_hi:[1,0] neg_lo:[0,1] neg_hi:[0,1]
	v_add_f32_e32 v1, v68, v1
	v_pk_mul_f32 v[138:139], v[86:87], v[86:87]
	v_add_f32_e32 v1, v69, v1
	v_pk_add_f32 v[140:141], v[74:75], v[72:73] op_sel_hi:[1,0] neg_lo:[0,1] neg_hi:[0,1]
	v_add_f32_e32 v1, v139, v1
	v_pk_mul_f32 v[72:73], v[140:141], v[140:141]
	v_add_f32_e32 v1, v138, v1
	v_add_f32_e32 v1, v73, v1
	v_add_f32_e32 v1, v72, v1
	v_mov_b32_e32 v68, v1
	s_nop 1
	v_permlane32_swap_b32 v68, v1
	v_add_f32_e32 v1, v1, v68
	v_mov_b32_e32 v68, v1
	s_nop 1
	v_permlane16_swap_b32 v68, v1
	v_add_f32_e32 v1, v1, v68
	s_nop 1
	v_add_f32_dpp v1, v1, v1 quad_perm:[1,0,3,2] row_mask:0xf bank_mask:0xf
	s_nop 1
	v_add_f32_dpp v1, v1, v1 quad_perm:[2,3,0,1] row_mask:0xf bank_mask:0xf
	s_nop 1
	v_add_f32_dpp v1, v1, v1 row_half_mirror row_mask:0xf bank_mask:0xf
	s_nop 1
	v_add_f32_dpp v1, v1, v1 row_mirror row_mask:0xf bank_mask:0xf
	v_fmamk_f32 v1, v1, 0x3a000000, v213
	v_cmp_gt_f32_e32 vcc, s12, v1
	v_mul_f32_e32 v68, 0x4b800000, v1
	s_nop 0
	v_cndmask_b32_e32 v1, v1, v68, vcc
	v_rsq_f32_e32 v1, v1
	s_nop 0
	v_mul_f32_e32 v68, 0x45800000, v1
	v_cndmask_b32_e32 v110, v1, v68, vcc
	v_pk_mul_f32 v[68:69], v[92:93], v[110:111] op_sel_hi:[1,0]
	v_pk_mul_f32 v[72:73], v[94:95], v[110:111] op_sel_hi:[1,0]
	v_pk_mul_f32 v[76:77], v[90:91], v[110:111] op_sel_hi:[1,0]
	v_pk_fma_f32 v[74:75], v[10:11], v[72:73], v[18:19]
	v_pk_fma_f32 v[72:73], v[8:9], v[68:69], v[16:17]
	v_pk_mul_f32 v[68:69], v[88:89], v[110:111] op_sel_hi:[1,0]
	v_pk_fma_f32 v[78:79], v[6:7], v[76:77], v[14:15]
	v_pk_fma_f32 v[76:77], v[4:5], v[68:69], v[12:13]
	global_store_dwordx4 v[70:71], v[72:75], off nt
	global_store_dwordx4 v[70:71], v[76:79], off offset:16 nt
	v_pk_mul_f32 v[68:69], v[102:103], v[110:111] op_sel_hi:[1,0]
	v_pk_mul_f32 v[72:73], v[104:105], v[110:111] op_sel_hi:[1,0]
	v_pk_mul_f32 v[76:77], v[98:99], v[110:111] op_sel_hi:[1,0]
	v_pk_fma_f32 v[74:75], v[26:27], v[72:73], v[34:35]
	v_pk_fma_f32 v[72:73], v[24:25], v[68:69], v[32:33]
	v_pk_mul_f32 v[68:69], v[96:97], v[110:111] op_sel_hi:[1,0]
	v_pk_fma_f32 v[78:79], v[22:23], v[76:77], v[30:31]
	v_pk_fma_f32 v[76:77], v[20:21], v[68:69], v[28:29]
	global_store_dwordx4 v[70:71], v[72:75], off offset:2048 nt
	global_store_dwordx4 v[70:71], v[76:79], off offset:2064 nt
	v_pk_mul_f32 v[68:69], v[82:83], v[110:111] op_sel_hi:[1,0]
	v_pk_mul_f32 v[72:73], v[128:129], v[110:111] op_sel_hi:[1,0]
	v_add_co_u32_e32 v82, vcc, s11, v70
	v_pk_fma_f32 v[74:75], v[38:39], v[72:73], v[46:47]
	v_pk_fma_f32 v[72:73], v[36:37], v[68:69], v[44:45]
	v_pk_mul_f32 v[68:69], v[100:101], v[110:111] op_sel_hi:[1,0]
	v_pk_mul_f32 v[76:77], v[132:133], v[110:111] op_sel_hi:[1,0]
	v_addc_co_u32_e32 v83, vcc, 0, v71, vcc
	v_pk_fma_f32 v[78:79], v[42:43], v[76:77], v[50:51]
	v_pk_fma_f32 v[76:77], v[40:41], v[68:69], v[48:49]
	global_store_dwordx4 v[82:83], v[72:75], off nt
	global_store_dwordx4 v[82:83], v[76:79], off offset:16 nt
	v_cmp_lt_i32_e32 vcc, s13, v0
	v_pk_mul_f32 v[72:73], v[80:81], v[110:111] op_sel_hi:[1,0]
	v_pk_mul_f32 v[74:75], v[136:137], v[110:111] op_sel_hi:[1,0]
	v_pk_mul_f32 v[68:69], v[86:87], v[110:111] op_sel_hi:[1,0]
	v_pk_mul_f32 v[70:71], v[140:141], v[110:111] op_sel_hi:[1,0]
	v_pk_fma_f32 v[74:75], v[54:55], v[74:75], v[62:63]
	v_pk_fma_f32 v[72:73], v[52:53], v[72:73], v[60:61]
	s_or_b64 s[2:3], vcc, s[2:3]
	v_pk_fma_f32 v[68:69], v[56:57], v[68:69], v[64:65] op_sel:[0,1,0] op_sel_hi:[1,0,1]
	v_pk_fma_f32 v[70:71], v[58:59], v[70:71], v[66:67] op_sel:[0,1,0] op_sel_hi:[1,0,1]
	global_store_dwordx4 v[82:83], v[72:75], off offset:2048 nt
	global_store_dwordx4 v[82:83], v[68:71], off offset:2064 nt
	s_andn2_b64 exec, exec, s[2:3]
	s_cbranch_execnz .LBB0_31

; __device__ __forceinline__ float bflo(unsigned u) { return __uint_as_float(u << 16); }
; __device__ __forceinline__ float bfhi(unsigned u) { return __uint_as_float(u & 0xffff0000u); }
; __device__ void ln_phase2(const bf16_t* __restrict__ mix, const float* __restrict__ Rf, const bf16_t* __restrict__ Rb, const float* __restrict__ gam, const float* __restrict__ bet, bf16_t* ob, float* of) {
;     ...
;     for (int row = blockIdx.x * 8 + wid; row < T_TOK; row += gridDim.x * 8) {
;         const size_t ro = (size_t)row * DM + lane * 8;
;         float v[32]; float s = 0.f;
; #pragma unroll
;         for (int j = 0; j < 4; ++j) {
;             const u32x4 m = *(const u32x4*)(mix + ro + 512 * j);
;             float r[8];
;             if (Rf) { const f32x4 a = *(const f32x4*)(Rf + ro + 512 * j), b = *(const f32x4*)(Rf + ro + 512 * j + 4);
;                 r[0] = a[0]; r[1] = a[1]; r[2] = a[2]; r[3] = a[3]; r[4] = b[0]; r[5] = b[1]; r[6] = b[2]; r[7] = b[3]; }
;             else { const u32x4 rb = *(const u32x4*)(Rb + ro + 512 * j);
;                 r[0] = bflo(rb.x); r[1] = bfhi(rb.x); r[2] = bflo(rb.y); r[3] = bfhi(rb.y); r[4] = bflo(rb.z); r[5] = bfhi(rb.z); r[6] = bflo(rb.w); r[7] = bfhi(rb.w); }
;             v[8 * j + 0] = DN_ALPHA * r[0] + bflo(m.x); v[8 * j + 1] = DN_ALPHA * r[1] + bfhi(m.x); v[8 * j + 2] = DN_ALPHA * r[2] + bflo(m.y); v[8 * j + 3] = DN_ALPHA * r[3] + bfhi(m.y);
;             v[8 * j + 4] = DN_ALPHA * r[4] + bflo(m.z); v[8 * j + 5] = DN_ALPHA * r[5] + bfhi(m.z); v[8 * j + 6] = DN_ALPHA * r[6] + bflo(m.w); v[8 * j + 7] = DN_ALPHA * r[7] + bfhi(m.w);
; #pragma unroll
;             for (int e = 0; e < 8; ++e) s += v[8 * j + e];
;         }
; #pragma unroll
;         for (int o = 32; o; o >>= 1) s += __shfl_xor(s, o);
.LBB0_93:
	v_ashrrev_i32_e32 v1, 31, v0
	v_lshlrev_b64 v[68:69], 11, v[0:1]
	v_or_b32_e32 v68, v68, v100
	v_lshlrev_b64 v[106:107], 1, v[68:69]
	v_lshl_add_u64 v[68:69], v[68:69], 2, s[72:73]
	v_add_co_u32_e32 v102, vcc, s9, v68
	v_lshl_add_u64 v[70:71], s[26:27], 0, v[106:107]
	v_lshl_add_u64 v[76:77], v[68:69], 0, s[12:13]
	v_addc_co_u32_e32 v103, vcc, 0, v69, vcc
	global_load_dwordx4 v[118:121], v[70:71], off
	global_load_dwordx4 v[122:125], v[68:69], off nt
	global_load_dwordx4 v[110:113], v[68:69], off offset:16 nt
	global_load_dwordx4 v[88:91], v[70:71], off offset:1024
	global_load_dwordx4 v[92:95], v[68:69], off offset:2048 nt
	global_load_dwordx4 v[96:99], v[68:69], off offset:2064 nt
	global_load_dwordx4 v[72:75], v[70:71], off offset:2048
	global_load_dwordx4 v[80:83], v[102:103], off nt
	global_load_dwordx4 v[84:87], v[76:77], off offset:16 nt
	s_nop 0
	global_load_dwordx4 v[76:79], v[70:71], off offset:3072
	v_lshl_add_u64 v[104:105], v[68:69], 0, s[16:17]
	global_load_dwordx4 v[68:71], v[102:103], off offset:2048 nt
	s_nop 0
	global_load_dwordx4 v[102:105], v[104:105], off offset:16 nt
	v_add_u32_e32 v0, s8, v0
	s_waitcnt vmcnt(0)
	v_and_b32_e32 v109, 0xffff0000, v78
	v_lshlrev_b32_e32 v108, 16, v78
	v_pk_fma_f32 v[102:103], v[102:103], s[22:23], v[108:109] op_sel_hi:[1,0,1]
	v_and_b32_e32 v109, 0xffff0000, v79
	v_lshlrev_b32_e32 v108, 16, v79
	v_lshl_add_u64 v[78:79], s[64:65], 0, v[106:107]
	v_lshlrev_b32_e32 v106, 16, v121
	v_and_b32_e32 v107, 0xffff0000, v121
	v_pk_fma_f32 v[106:107], v[112:113], s[22:23], v[106:107] op_sel_hi:[1,0,1]
	v_lshlrev_b32_e32 v112, 16, v120
	v_and_b32_e32 v113, 0xffff0000, v120
	v_pk_fma_f32 v[110:111], v[110:111], s[22:23], v[112:113] op_sel_hi:[1,0,1]
	v_lshlrev_b32_e32 v112, 16, v118
	v_and_b32_e32 v113, 0xffff0000, v118
	v_pk_fma_f32 v[112:113], v[122:123], s[22:23], v[112:113] op_sel_hi:[1,0,1]
	v_pk_fma_f32 v[104:105], v[104:105], s[22:23], v[108:109] op_sel_hi:[1,0,1]
	v_lshlrev_b32_e32 v108, 16, v119
	v_and_b32_e32 v109, 0xffff0000, v119
	v_add_f32_e32 v1, 0, v112
	v_pk_fma_f32 v[108:109], v[124:125], s[22:23], v[108:109] op_sel_hi:[1,0,1]
	v_add_f32_e32 v1, v113, v1
	v_add_f32_e32 v1, v108, v1
	v_add_f32_e32 v1, v109, v1
	v_lshlrev_b32_e32 v118, 16, v91
	v_and_b32_e32 v119, 0xffff0000, v91
	v_add_f32_e32 v1, v110, v1
	v_pk_fma_f32 v[98:99], v[98:99], s[22:23], v[118:119] op_sel_hi:[1,0,1]
	v_lshlrev_b32_e32 v118, 16, v89
	v_and_b32_e32 v119, 0xffff0000, v89
	v_add_f32_e32 v1, v111, v1
	v_pk_fma_f32 v[94:95], v[94:95], s[22:23], v[118:119] op_sel_hi:[1,0,1]
	v_lshlrev_b32_e32 v118, 16, v90
	v_and_b32_e32 v119, 0xffff0000, v90
	v_add_f32_e32 v1, v106, v1
	v_pk_fma_f32 v[90:91], v[96:97], s[22:23], v[118:119] op_sel_hi:[1,0,1]
	v_lshlrev_b32_e32 v96, 16, v88
	v_and_b32_e32 v97, 0xffff0000, v88
	v_add_f32_e32 v1, v107, v1
	v_pk_fma_f32 v[88:89], v[92:93], s[22:23], v[96:97] op_sel_hi:[1,0,1]
	v_lshlrev_b32_e32 v92, 16, v75
	v_add_f32_e32 v1, v1, v88
	v_add_f32_e32 v1, v89, v1
	v_add_f32_e32 v1, v94, v1
	v_add_f32_e32 v1, v95, v1
	v_and_b32_e32 v93, 0xffff0000, v75
	v_add_f32_e32 v1, v90, v1
	v_pk_fma_f32 v[86:87], v[86:87], s[22:23], v[92:93] op_sel_hi:[1,0,1]
	v_lshlrev_b32_e32 v92, 16, v73
	v_and_b32_e32 v93, 0xffff0000, v73
	v_add_f32_e32 v1, v91, v1
	v_pk_fma_f32 v[82:83], v[82:83], s[22:23], v[92:93] op_sel_hi:[1,0,1]
	v_lshlrev_b32_e32 v92, 16, v74
	v_and_b32_e32 v93, 0xffff0000, v74
	v_add_f32_e32 v1, v98, v1
	v_pk_fma_f32 v[74:75], v[84:85], s[22:23], v[92:93] op_sel_hi:[1,0,1]
	v_lshlrev_b32_e32 v84, 16, v72
	v_and_b32_e32 v85, 0xffff0000, v72
	v_add_f32_e32 v1, v99, v1
	v_pk_fma_f32 v[72:73], v[80:81], s[22:23], v[84:85] op_sel_hi:[1,0,1]
	v_lshlrev_b32_e32 v80, 16, v77
	v_add_f32_e32 v1, v1, v72
	v_add_f32_e32 v1, v73, v1
	v_add_f32_e32 v1, v82, v1
	v_add_f32_e32 v1, v83, v1
	v_add_f32_e32 v1, v74, v1
	v_add_f32_e32 v1, v75, v1
	v_and_b32_e32 v81, 0xffff0000, v77
	v_add_f32_e32 v1, v86, v1
	v_pk_fma_f32 v[70:71], v[70:71], s[22:23], v[80:81] op_sel_hi:[1,0,1]
	v_lshlrev_b32_e32 v80, 16, v76
	v_and_b32_e32 v81, 0xffff0000, v76
	v_add_f32_e32 v1, v87, v1
	v_pk_fma_f32 v[68:69], v[68:69], s[22:23], v[80:81] op_sel_hi:[1,0,1]
	s_nop 0
	v_add_f32_e32 v1, v1, v68
	v_add_f32_e32 v1, v69, v1
	v_add_f32_e32 v1, v70, v1
	v_add_f32_e32 v1, v71, v1
	v_add_f32_e32 v1, v102, v1
	v_add_f32_e32 v1, v103, v1
	v_add_f32_e32 v1, v104, v1
	v_add_f32_e32 v1, v105, v1
	v_mov_b32_e32 v76, v1
	s_nop 1
	v_permlane32_swap_b32 v76, v1
	v_add_f32_e32 v1, v1, v76
	v_mov_b32_e32 v76, v1
	s_nop 1
	v_permlane16_swap_b32 v76, v1
	v_add_f32_e32 v1, v1, v76
	s_nop 1
	v_add_f32_dpp v1, v1, v1 quad_perm:[1,0,3,2] row_mask:0xf bank_mask:0xf
	s_nop 1
	v_add_f32_dpp v1, v1, v1 quad_perm:[2,3,0,1] row_mask:0xf bank_mask:0xf
	s_nop 1
	v_add_f32_dpp v1, v1, v1 row_half_mirror row_mask:0xf bank_mask:0xf
	s_nop 1
	v_add_f32_dpp v1, v1, v1 row_mirror row_mask:0xf bank_mask:0xf
	v_mul_f32_e32 v92, 0x3a000000, v1
	v_pk_add_f32 v[96:97], v[112:113], v[92:93] op_sel_hi:[1,0] neg_lo:[0,1] neg_hi:[0,1]
	v_pk_add_f32 v[108:109], v[108:109], v[92:93] op_sel_hi:[1,0] neg_lo:[0,1] neg_hi:[0,1]
	v_pk_mul_f32 v[112:113], v[96:97], v[96:97]
	v_pk_mul_f32 v[118:119], v[108:109], v[108:109]
	v_add_f32_e32 v1, v112, v113
	v_pk_add_f32 v[110:111], v[110:111], v[92:93] op_sel_hi:[1,0] neg_lo:[0,1] neg_hi:[0,1]
	v_add_f32_e32 v1, v118, v1
	v_pk_mul_f32 v[120:121], v[110:111], v[110:111]
	v_add_f32_e32 v1, v119, v1
	v_pk_add_f32 v[106:107], v[106:107], v[92:93] op_sel_hi:[1,0] neg_lo:[0,1] neg_hi:[0,1]
	v_add_f32_e32 v1, v120, v1
	v_pk_mul_f32 v[122:123], v[106:107], v[106:107]
	v_add_f32_e32 v1, v121, v1
; __device__ __forceinline__ unsigned cvt_pk_bf16(float lo, float hi) { const f32x2v v = {lo, hi}; const b16x2v r = __builtin_convertvector(v, b16x2v); return __builtin_bit_cast(unsigned, r); }
; __device__ void ln_phase2(const bf16_t* __restrict__ mix, const float* __restrict__ Rf, const bf16_t* __restrict__ Rb, const float* __restrict__ gam, const float* __restrict__ bet, bf16_t* ob, float* of) {
;     ...
;         float q = 0.f;
; #pragma unroll
;         for (int e = 0; e < 32; ++e) { const float dlt = v[e] - mean; q += dlt * dlt; }
; #pragma unroll
;         for (int o = 32; o; o >>= 1) q += __shfl_xor(q, o);
;         const float rstd = rsqrtf(q * (1.0f / 2048.0f) + 1e-5f);
; #pragma unroll
;         for (int j = 0; j < 4; ++j) {
;             const f32x4 g0 = *(const f32x4*)(gam + lane * 8 + 512 * j), g1 = *(const f32x4*)(gam + lane * 8 + 512 * j + 4);
;             const f32x4 b0 = *(const f32x4*)(bet + lane * 8 + 512 * j), b1 = *(const f32x4*)(bet + lane * 8 + 512 * j + 4);
;             f32x4 y0, y1;
; #pragma unroll
;             for (int e = 0; e < 4; ++e) { y0[e] = (v[8 * j + e] - mean) * rstd * g0[e] + b0[e]; y1[e] = (v[8 * j + 4 + e] - mean) * rstd * g1[e] + b1[e]; }
;             if (ob) { u32x4 w; w.x = cvt_pk_bf16(y0[0], y0[1]); w.y = cvt_pk_bf16(y0[2], y0[3]); w.z = cvt_pk_bf16(y1[0], y1[1]); w.w = cvt_pk_bf16(y1[2], y1[3]); *(u32x4*)(ob + ro + 512 * j) = w; }
;             else { *(f32x4*)(of + ro + 512 * j) = y0; *(f32x4*)(of + ro + 512 * j + 4) = y1; }
;         }
	v_pk_add_f32 v[124:125], v[88:89], v[92:93] op_sel_hi:[1,0] neg_lo:[0,1] neg_hi:[0,1]
	v_add_f32_e32 v1, v122, v1
	v_pk_mul_f32 v[88:89], v[124:125], v[124:125]
	v_add_f32_e32 v1, v123, v1
	v_pk_add_f32 v[94:95], v[94:95], v[92:93] op_sel_hi:[1,0] neg_lo:[0,1] neg_hi:[0,1]
	v_add_f32_e32 v1, v88, v1
	v_pk_mul_f32 v[126:127], v[94:95], v[94:95]
	v_add_f32_e32 v1, v89, v1
	v_pk_add_f32 v[90:91], v[90:91], v[92:93] op_sel_hi:[1,0] neg_lo:[0,1] neg_hi:[0,1]
	v_add_f32_e32 v1, v126, v1
	v_pk_mul_f32 v[128:129], v[90:91], v[90:91]
	v_add_f32_e32 v1, v127, v1
	v_pk_add_f32 v[98:99], v[98:99], v[92:93] op_sel_hi:[1,0] neg_lo:[0,1] neg_hi:[0,1]
	v_add_f32_e32 v1, v128, v1
	v_pk_mul_f32 v[130:131], v[98:99], v[98:99]
	v_add_f32_e32 v1, v129, v1
	v_pk_add_f32 v[80:81], v[72:73], v[92:93] op_sel_hi:[1,0] neg_lo:[0,1] neg_hi:[0,1]
	v_add_f32_e32 v1, v130, v1
	v_pk_mul_f32 v[132:133], v[80:81], v[80:81]
	v_add_f32_e32 v1, v131, v1
	v_pk_add_f32 v[76:77], v[82:83], v[92:93] op_sel_hi:[1,0] neg_lo:[0,1] neg_hi:[0,1]
	v_add_f32_e32 v1, v132, v1
	v_pk_mul_f32 v[134:135], v[76:77], v[76:77]
	v_add_f32_e32 v1, v133, v1
	v_pk_add_f32 v[84:85], v[74:75], v[92:93] op_sel_hi:[1,0] neg_lo:[0,1] neg_hi:[0,1]
	v_add_f32_e32 v1, v134, v1
	v_pk_mul_f32 v[136:137], v[84:85], v[84:85]
	v_add_f32_e32 v1, v135, v1
	v_pk_add_f32 v[82:83], v[86:87], v[92:93] op_sel_hi:[1,0] neg_lo:[0,1] neg_hi:[0,1]
	v_add_f32_e32 v1, v136, v1
	v_pk_mul_f32 v[86:87], v[82:83], v[82:83]
	v_add_f32_e32 v1, v137, v1
	v_pk_add_f32 v[68:69], v[68:69], v[92:93] op_sel_hi:[1,0] neg_lo:[0,1] neg_hi:[0,1]
	v_add_f32_e32 v1, v86, v1
	v_pk_mul_f32 v[138:139], v[68:69], v[68:69]
	v_add_f32_e32 v1, v87, v1
	v_pk_add_f32 v[70:71], v[70:71], v[92:93] op_sel_hi:[1,0] neg_lo:[0,1] neg_hi:[0,1]
	v_add_f32_e32 v1, v138, v1
	v_pk_mul_f32 v[140:141], v[70:71], v[70:71]
	v_add_f32_e32 v1, v139, v1
	v_pk_add_f32 v[74:75], v[102:103], v[92:93] op_sel_hi:[1,0] neg_lo:[0,1] neg_hi:[0,1]
	v_add_f32_e32 v1, v140, v1
	v_pk_add_f32 v[72:73], v[104:105], v[92:93] op_sel_hi:[1,0] neg_lo:[0,1] neg_hi:[0,1]
	v_pk_mul_f32 v[92:93], v[74:75], v[74:75]
	v_add_f32_e32 v1, v141, v1
	v_add_f32_e32 v1, v92, v1
	v_pk_mul_f32 v[104:105], v[72:73], v[72:73]
	v_add_f32_e32 v1, v93, v1
	v_add_f32_e32 v1, v104, v1
	v_add_f32_e32 v1, v105, v1
	v_mov_b32_e32 v86, v1
	s_nop 1
	v_permlane32_swap_b32 v86, v1
	v_add_f32_e32 v1, v1, v86
	v_mov_b32_e32 v86, v1
	s_nop 1
	v_permlane16_swap_b32 v86, v1
	v_add_f32_e32 v1, v1, v86
	s_nop 1
	v_add_f32_dpp v1, v1, v1 quad_perm:[1,0,3,2] row_mask:0xf bank_mask:0xf
	s_nop 1
	v_add_f32_dpp v1, v1, v1 quad_perm:[2,3,0,1] row_mask:0xf bank_mask:0xf
	s_nop 1
	v_add_f32_dpp v1, v1, v1 row_half_mirror row_mask:0xf bank_mask:0xf
	s_nop 1
	v_add_f32_dpp v1, v1, v1 row_mirror row_mask:0xf bank_mask:0xf
	v_fmamk_f32 v1, v1, 0x3a000000, v213
	v_cmp_gt_f32_e32 vcc, s15, v1
	v_mul_f32_e32 v86, 0x4b800000, v1
	s_nop 0
	v_cndmask_b32_e32 v1, v1, v86, vcc
	v_rsq_f32_e32 v1, v1
	s_nop 0
	v_mul_f32_e32 v86, 0x45800000, v1
	v_cndmask_b32_e32 v92, v1, v86, vcc
	v_pk_mul_f32 v[86:87], v[96:97], v[92:93] op_sel_hi:[1,0]
	v_pk_mul_f32 v[88:89], v[110:111], v[92:93] op_sel_hi:[1,0]
	v_pk_mul_f32 v[96:97], v[108:109], v[92:93] op_sel_hi:[1,0]
	v_pk_mul_f32 v[102:103], v[106:107], v[92:93] op_sel_hi:[1,0]
	v_pk_fma_f32 v[86:87], v[4:5], v[86:87], v[8:9]
	v_pk_fma_f32 v[88:89], v[12:13], v[88:89], v[16:17]
	v_pk_fma_f32 v[96:97], v[6:7], v[96:97], v[10:11]
	v_pk_fma_f32 v[102:103], v[14:15], v[102:103], v[18:19]
	v_cvt_pk_bf16_f32 v86, v86, v87
	v_cvt_pk_bf16_f32 v87, v96, v97
	v_cvt_pk_bf16_f32 v88, v88, v89
	v_cvt_pk_bf16_f32 v89, v102, v103
	global_store_dwordx4 v[78:79], v[86:89], off
	v_pk_mul_f32 v[80:81], v[80:81], v[92:93] op_sel_hi:[1,0]
	v_pk_mul_f32 v[84:85], v[84:85], v[92:93] op_sel_hi:[1,0]
	v_pk_mul_f32 v[86:87], v[124:125], v[92:93] op_sel_hi:[1,0]
	v_pk_mul_f32 v[88:89], v[90:91], v[92:93] op_sel_hi:[1,0]
	v_pk_mul_f32 v[90:91], v[94:95], v[92:93] op_sel_hi:[1,0]
	v_pk_mul_f32 v[94:95], v[98:99], v[92:93] op_sel_hi:[1,0]
	v_pk_fma_f32 v[86:87], v[20:21], v[86:87], v[24:25]
	v_pk_fma_f32 v[88:89], v[28:29], v[88:89], v[32:33]
	v_pk_fma_f32 v[90:91], v[22:23], v[90:91], v[26:27]
	v_pk_fma_f32 v[94:95], v[30:31], v[94:95], v[34:35]
	v_cvt_pk_bf16_f32 v86, v86, v87
	v_cvt_pk_bf16_f32 v87, v90, v91
	v_cvt_pk_bf16_f32 v88, v88, v89
	v_cvt_pk_bf16_f32 v89, v94, v95
	v_pk_mul_f32 v[76:77], v[76:77], v[92:93] op_sel_hi:[1,0]
	v_pk_mul_f32 v[82:83], v[82:83], v[92:93] op_sel_hi:[1,0]
	v_pk_mul_f32 v[68:69], v[68:69], v[92:93] op_sel_hi:[1,0]
	v_pk_mul_f32 v[74:75], v[74:75], v[92:93] op_sel_hi:[1,0]
	v_pk_mul_f32 v[70:71], v[70:71], v[92:93] op_sel_hi:[1,0]
	v_pk_mul_f32 v[72:73], v[72:73], v[92:93] op_sel_hi:[1,0]
	global_store_dwordx4 v[78:79], v[86:89], off offset:1024
	v_pk_fma_f32 v[80:81], v[36:37], v[80:81], v[44:45]
	v_pk_fma_f32 v[84:85], v[40:41], v[84:85], v[48:49]
	v_pk_fma_f32 v[76:77], v[38:39], v[76:77], v[46:47]
	v_pk_fma_f32 v[86:87], v[42:43], v[82:83], v[50:51]
	v_pk_fma_f32 v[68:69], v[52:53], v[68:69], v[60:61]
	v_pk_fma_f32 v[74:75], v[56:57], v[74:75], v[64:65]
	v_pk_fma_f32 v[70:71], v[54:55], v[70:71], v[62:63]
	v_pk_fma_f32 v[72:73], v[58:59], v[72:73], v[66:67]
	v_cmp_lt_i32_e32 vcc, s18, v0
	v_cvt_pk_bf16_f32 v80, v80, v81
	v_cvt_pk_bf16_f32 v81, v76, v77
	v_cvt_pk_bf16_f32 v82, v84, v85
	v_cvt_pk_bf16_f32 v83, v86, v87
	v_cvt_pk_bf16_f32 v68, v68, v69
	v_cvt_pk_bf16_f32 v69, v70, v71
	v_cvt_pk_bf16_f32 v70, v74, v75
	v_cvt_pk_bf16_f32 v71, v72, v73
	s_or_b64 s[2:3], vcc, s[2:3]
	global_store_dwordx4 v[78:79], v[80:83], off offset:2048
	global_store_dwordx4 v[78:79], v[68:71], off offset:3072
	s_andn2_b64 exec, exec, s[2:3]
	s_cbranch_execnz .LBB0_93

; __device__ __forceinline__ unsigned cvt_pk_bf16(float lo, float hi) { const f32x2v v = {lo, hi}; const b16x2v r = __builtin_convertvector(v, b16x2v); return __builtin_bit_cast(unsigned, r); }
; __device__ void prep_phase(const Params& p, unsigned char* smem_g) {
;     ...
;         for (int ks = 0; ks < 8; ++ks) {
;             float v[8];
; #pragma unroll
;             for (int e = 0; e < 8; ++e) v[e] = p.w_in[(size_t)(256 * wk + 32 * ks + 8 * g + e) * 6160 + 3072 + idx];
;             u32x4 w; w.x = cvt_pk_bf16(v[0], v[1]); w.y = cvt_pk_bf16(v[2], v[3]); w.z = cvt_pk_bf16(v[4], v[5]); w.w = cvt_pk_bf16(v[6], v[7]);
;             bfr[ks] = __builtin_bit_cast(bf16x8, w);
;         }
;         f32x4 acc[4];
; #pragma unroll
;         for (int mt = 0; mt < 4; ++mt) {
;             acc[mt] = (f32x4){0.f, 0.f, 0.f, 0.f};
; #pragma unroll
;             for (int ks = 0; ks < 8; ++ks) {
;                 const size_t off = (size_t)(t0 + 16 * ((mt + mrot) & 3) + idx) * DM + 256 * wk + 32 * ks + 8 * g;
;                 const f32x4 a = *(const f32x4*)(p.x + off), b = *(const f32x4*)(p.x + off + 4);
;                 u32x4 w; w.x = cvt_pk_bf16(a[0], a[1]); w.y = cvt_pk_bf16(a[2], a[3]); w.z = cvt_pk_bf16(b[0], b[1]); w.w = cvt_pk_bf16(b[2], b[3]);
;                 *(u32x4*)(xb + off) = w;
.LBB0_142:
	s_lshl_b32 s0, s3, 6
	s_mov_b32 s4, 0
	s_add_i32 s5, 0, 0x8000
	global_load_dword v52, v[52:53], off
	global_load_dword v54, v[54:55], off
	global_load_dword v56, v[56:57], off
	global_load_dword v58, v[58:59], off
	global_load_dword v60, v[60:61], off
	global_load_dword v62, v[62:63], off
	global_load_dword v64, v[64:65], off
	global_load_dword v66, v[66:67], off
	global_load_dword v68, v[68:69], off
	global_load_dword v70, v[70:71], off
	global_load_dword v72, v[72:73], off
	global_load_dword v74, v[74:75], off
	global_load_dword v76, v[76:77], off
	global_load_dword v78, v[78:79], off
	global_load_dword v80, v[80:81], off
	global_load_dword v82, v[82:83], off
	global_load_dword v84, v[84:85], off
	global_load_dword v86, v[86:87], off
	global_load_dword v88, v[88:89], off
	global_load_dword v90, v[90:91], off
	global_load_dword v92, v[92:93], off
	global_load_dword v94, v[94:95], off
	global_load_dword v96, v[96:97], off
	global_load_dword v98, v[98:99], off
	global_load_dword v100, v[100:101], off
	global_load_dword v102, v[102:103], off
	global_load_dword v104, v[104:105], off
	global_load_dword v106, v[106:107], off
	global_load_dword v108, v[108:109], off
	global_load_dword v110, v[110:111], off
	global_load_dword v112, v[112:113], off
	global_load_dword v114, v[114:115], off
	global_load_dword v116, v[116:117], off
	global_load_dword v118, v[118:119], off
	global_load_dword v120, v[120:121], off
	global_load_dword v122, v[122:123], off
	global_load_dword v124, v[124:125], off
	global_load_dword v126, v[126:127], off
	global_load_dword v128, v[128:129], off
	global_load_dword v130, v[130:131], off
	global_load_dword v132, v[132:133], off
	global_load_dword v134, v[134:135], off
	global_load_dword v136, v[136:137], off
	global_load_dword v138, v[138:139], off
	global_load_dword v140, v[140:141], off
	global_load_dword v142, v[142:143], off
	global_load_dword v144, v[144:145], off
	global_load_dword v146, v[146:147], off
	global_load_dword v148, v[148:149], off
	global_load_dword v150, v[150:151], off
	global_load_dword v152, v[152:153], off
	global_load_dword v154, v[154:155], off
	global_load_dword v156, v[156:157], off
	global_load_dword v158, v[158:159], off
	global_load_dword v160, v[160:161], off
	global_load_dword v162, v[162:163], off
	global_load_dword v164, v[164:165], off
	global_load_dword v166, v[166:167], off
	global_load_dword v168, v[168:169], off
	global_load_dword v170, v[170:171], off
	global_load_dword v172, v[172:173], off
	global_load_dword v174, v[174:175], off
	global_load_dword v176, v[176:177], off
	global_load_dword v178, v[178:179], off
	s_waitcnt vmcnt(0)
	v_cvt_pk_bf16_f32 v32, v52, v54
	v_cvt_pk_bf16_f32 v33, v56, v58
	v_cvt_pk_bf16_f32 v34, v60, v62
	v_cvt_pk_bf16_f32 v35, v64, v66
	v_cvt_pk_bf16_f32 v28, v68, v70
	v_cvt_pk_bf16_f32 v29, v72, v74
	v_cvt_pk_bf16_f32 v30, v76, v78
	v_cvt_pk_bf16_f32 v31, v80, v82
	v_cvt_pk_bf16_f32 v24, v84, v86
	v_cvt_pk_bf16_f32 v25, v88, v90
	v_cvt_pk_bf16_f32 v26, v92, v94
	v_cvt_pk_bf16_f32 v27, v96, v98
	v_cvt_pk_bf16_f32 v20, v100, v102
	v_cvt_pk_bf16_f32 v21, v104, v106
	v_cvt_pk_bf16_f32 v22, v108, v110
	v_cvt_pk_bf16_f32 v23, v112, v114
	v_cvt_pk_bf16_f32 v16, v116, v118
	v_cvt_pk_bf16_f32 v17, v120, v122
	v_cvt_pk_bf16_f32 v18, v124, v126
	v_cvt_pk_bf16_f32 v19, v128, v130
	v_cvt_pk_bf16_f32 v12, v132, v134
	v_cvt_pk_bf16_f32 v13, v136, v138
	v_cvt_pk_bf16_f32 v14, v140, v142
	v_cvt_pk_bf16_f32 v15, v144, v146
	v_cvt_pk_bf16_f32 v8, v148, v150
	v_cvt_pk_bf16_f32 v9, v152, v154
	v_cvt_pk_bf16_f32 v10, v156, v158
	v_cvt_pk_bf16_f32 v11, v160, v162
	v_cvt_pk_bf16_f32 v4, v164, v166
	v_cvt_pk_bf16_f32 v5, v168, v170
	v_cvt_pk_bf16_f32 v6, v172, v174
	v_cvt_pk_bf16_f32 v7, v176, v178
	v_or_b32_e32 v244, s0, v229
	v_ashrrev_i32_e32 v245, 31, v244
	v_lshlrev_b64 v[244:245], 11, v[244:245]
	v_or_b32_e32 v244, v244, v48
	v_lshl_add_u64 v[148:149], v[244:245], 2, s[72:73]
	v_lshl_add_u64 v[156:157], v[244:245], 1, s[92:93]
	v_or_b32_e32 v244, s0, v230
	v_ashrrev_i32_e32 v245, 31, v244
	v_lshlrev_b64 v[244:245], 11, v[244:245]
	v_or_b32_e32 v244, v244, v48
	v_lshl_add_u64 v[150:151], v[244:245], 2, s[72:73]
	v_lshl_add_u64 v[158:159], v[244:245], 1, s[92:93]
	v_or_b32_e32 v244, s0, v231
	v_ashrrev_i32_e32 v245, 31, v244
	v_lshlrev_b64 v[244:245], 11, v[244:245]
	v_or_b32_e32 v244, v244, v48
	v_lshl_add_u64 v[152:153], v[244:245], 2, s[72:73]
	v_lshl_add_u64 v[160:161], v[244:245], 1, s[92:93]
	v_or_b32_e32 v244, s0, v234
	v_ashrrev_i32_e32 v245, 31, v244
	v_lshlrev_b64 v[244:245], 11, v[244:245]
	v_or_b32_e32 v244, v244, v48
	v_lshl_add_u64 v[154:155], v[244:245], 2, s[72:73]
	v_lshl_add_u64 v[162:163], v[244:245], 1, s[92:93]
	global_load_dwordx4 v[52:55], v[148:149], off nt
	global_load_dwordx4 v[56:59], v[148:149], off offset:16 nt
	global_load_dwordx4 v[60:63], v[148:149], off offset:128 nt
	global_load_dwordx4 v[64:67], v[148:149], off offset:144 nt
	global_load_dwordx4 v[68:71], v[148:149], off offset:256 nt
	global_load_dwordx4 v[72:75], v[148:149], off offset:272 nt
	global_load_dwordx4 v[76:79], v[148:149], off offset:384 nt
	global_load_dwordx4 v[80:83], v[148:149], off offset:400 nt
	global_load_dwordx4 v[84:87], v[148:149], off offset:512 nt
	global_load_dwordx4 v[88:91], v[148:149], off offset:528 nt
	global_load_dwordx4 v[92:95], v[148:149], off offset:640 nt
	global_load_dwordx4 v[96:99], v[148:149], off offset:656 nt
	global_load_dwordx4 v[100:103], v[148:149], off offset:768 nt
	global_load_dwordx4 v[104:107], v[148:149], off offset:784 nt
	global_load_dwordx4 v[108:111], v[148:149], off offset:896 nt
	global_load_dwordx4 v[112:115], v[148:149], off offset:912 nt
	global_load_dwordx4 v[116:119], v[150:151], off nt
	global_load_dwordx4 v[120:123], v[150:151], off offset:16 nt
	global_load_dwordx4 v[124:127], v[150:151], off offset:128 nt
	global_load_dwordx4 v[128:131], v[150:151], off offset:144 nt
	global_load_dwordx4 v[132:135], v[150:151], off offset:256 nt
	global_load_dwordx4 v[136:139], v[150:151], off offset:272 nt
	global_load_dwordx4 v[140:143], v[150:151], off offset:384 nt
	global_load_dwordx4 v[144:147], v[150:151], off offset:400 nt
	s_waitcnt vmcnt(22)
; __device__ __forceinline__ unsigned cvt_pk_bf16(float lo, float hi) { const f32x2v v = {lo, hi}; const b16x2v r = __builtin_convertvector(v, b16x2v); return __builtin_bit_cast(unsigned, r); }
; __device__ __forceinline__ f32x4 mfma16(bf16x8 a, bf16x8 b, f32x4 c) { return __builtin_amdgcn_mfma_f32_16x16x32_bf16(a, b, c, 0, 0, 0); }
; __device__ void prep_phase(const Params& p, unsigned char* smem_g) {
;     ...
;         for (int mt = 0; mt < 4; ++mt) {
;             acc[mt] = (f32x4){0.f, 0.f, 0.f, 0.f};
; #pragma unroll
;             for (int ks = 0; ks < 8; ++ks) {
;                 const size_t off = (size_t)(t0 + 16 * ((mt + mrot) & 3) + idx) * DM + 256 * wk + 32 * ks + 8 * g;
;                 const f32x4 a = *(const f32x4*)(p.x + off), b = *(const f32x4*)(p.x + off + 4);
;                 u32x4 w; w.x = cvt_pk_bf16(a[0], a[1]); w.y = cvt_pk_bf16(a[2], a[3]); w.z = cvt_pk_bf16(b[0], b[1]); w.w = cvt_pk_bf16(b[2], b[3]);
;                 *(u32x4*)(xb + off) = w;
;                 acc[mt] = mfma16(__builtin_bit_cast(bf16x8, w), bfr[ks], acc[mt]);
;             }
;         }
	v_cvt_pk_bf16_f32 v236, v52, v53
	v_cvt_pk_bf16_f32 v237, v54, v55
	v_cvt_pk_bf16_f32 v238, v56, v57
	v_cvt_pk_bf16_f32 v239, v58, v59
	global_store_dwordx4 v[156:157], v[236:239], off
	s_nop 0
	v_mfma_f32_16x16x32_bf16 v[36:39], v[236:239], v[32:35], 0
	global_load_dwordx4 v[52:55], v[150:151], off offset:512 nt
	global_load_dwordx4 v[56:59], v[150:151], off offset:528 nt
	s_waitcnt vmcnt(23)
	v_cvt_pk_bf16_f32 v240, v60, v61
	v_cvt_pk_bf16_f32 v241, v62, v63
	v_cvt_pk_bf16_f32 v242, v64, v65
	v_cvt_pk_bf16_f32 v243, v66, v67
	global_store_dwordx4 v[156:157], v[240:243], off offset:64
	s_nop 0
	v_mfma_f32_16x16x32_bf16 v[36:39], v[240:243], v[28:31], v[36:39]
	global_load_dwordx4 v[60:63], v[150:151], off offset:640 nt
	global_load_dwordx4 v[64:67], v[150:151], off offset:656 nt
	s_waitcnt vmcnt(24)
	v_cvt_pk_bf16_f32 v236, v68, v69
	v_cvt_pk_bf16_f32 v237, v70, v71
	v_cvt_pk_bf16_f32 v238, v72, v73
	v_cvt_pk_bf16_f32 v239, v74, v75
	global_store_dwordx4 v[156:157], v[236:239], off offset:128
	s_nop 0
	v_mfma_f32_16x16x32_bf16 v[36:39], v[236:239], v[24:27], v[36:39]
	global_load_dwordx4 v[68:71], v[150:151], off offset:768 nt
	global_load_dwordx4 v[72:75], v[150:151], off offset:784 nt
	s_waitcnt vmcnt(25)
	v_cvt_pk_bf16_f32 v240, v76, v77
	v_cvt_pk_bf16_f32 v241, v78, v79
	v_cvt_pk_bf16_f32 v242, v80, v81
	v_cvt_pk_bf16_f32 v243, v82, v83
	global_store_dwordx4 v[156:157], v[240:243], off offset:192
	s_nop 0
	v_mfma_f32_16x16x32_bf16 v[36:39], v[240:243], v[20:23], v[36:39]
	global_load_dwordx4 v[76:79], v[150:151], off offset:896 nt
	global_load_dwordx4 v[80:83], v[150:151], off offset:912 nt
	s_waitcnt vmcnt(26)
	v_cvt_pk_bf16_f32 v236, v84, v85
	v_cvt_pk_bf16_f32 v237, v86, v87
	v_cvt_pk_bf16_f32 v238, v88, v89
	v_cvt_pk_bf16_f32 v239, v90, v91
	global_store_dwordx4 v[156:157], v[236:239], off offset:256
	s_nop 0
	v_mfma_f32_16x16x32_bf16 v[36:39], v[236:239], v[16:19], v[36:39]
	global_load_dwordx4 v[84:87], v[152:153], off nt
	global_load_dwordx4 v[88:91], v[152:153], off offset:16 nt
	s_waitcnt vmcnt(27)
	v_cvt_pk_bf16_f32 v240, v92, v93
	v_cvt_pk_bf16_f32 v241, v94, v95
	v_cvt_pk_bf16_f32 v242, v96, v97
	v_cvt_pk_bf16_f32 v243, v98, v99
	global_store_dwordx4 v[156:157], v[240:243], off offset:320
	s_nop 0
	v_mfma_f32_16x16x32_bf16 v[36:39], v[240:243], v[12:15], v[36:39]
	global_load_dwordx4 v[92:95], v[152:153], off offset:128 nt
	global_load_dwordx4 v[96:99], v[152:153], off offset:144 nt
	s_waitcnt vmcnt(28)
	v_cvt_pk_bf16_f32 v236, v100, v101
	v_cvt_pk_bf16_f32 v237, v102, v103
	v_cvt_pk_bf16_f32 v238, v104, v105
	v_cvt_pk_bf16_f32 v239, v106, v107
	global_store_dwordx4 v[156:157], v[236:239], off offset:384
	s_nop 0
	v_mfma_f32_16x16x32_bf16 v[36:39], v[236:239], v[8:11], v[36:39]
	global_load_dwordx4 v[100:103], v[152:153], off offset:256 nt
	global_load_dwordx4 v[104:107], v[152:153], off offset:272 nt
	s_waitcnt vmcnt(29)
	v_cvt_pk_bf16_f32 v240, v108, v109
	v_cvt_pk_bf16_f32 v241, v110, v111
	v_cvt_pk_bf16_f32 v242, v112, v113
	v_cvt_pk_bf16_f32 v243, v114, v115
	global_store_dwordx4 v[156:157], v[240:243], off offset:448
	s_nop 0
	v_mfma_f32_16x16x32_bf16 v[36:39], v[240:243], v[4:7], v[36:39]
	global_load_dwordx4 v[108:111], v[152:153], off offset:384 nt
	global_load_dwordx4 v[112:115], v[152:153], off offset:400 nt
	s_waitcnt vmcnt(30)
	v_cvt_pk_bf16_f32 v236, v116, v117
	v_cvt_pk_bf16_f32 v237, v118, v119
	v_cvt_pk_bf16_f32 v238, v120, v121
	v_cvt_pk_bf16_f32 v239, v122, v123
	global_store_dwordx4 v[158:159], v[236:239], off
	s_nop 0
	v_mfma_f32_16x16x32_bf16 v[40:43], v[236:239], v[32:35], 0
	global_load_dwordx4 v[116:119], v[152:153], off offset:512 nt
	global_load_dwordx4 v[120:123], v[152:153], off offset:528 nt
	s_waitcnt vmcnt(31)
	v_cvt_pk_bf16_f32 v240, v124, v125
	v_cvt_pk_bf16_f32 v241, v126, v127
	v_cvt_pk_bf16_f32 v242, v128, v129
	v_cvt_pk_bf16_f32 v243, v130, v131
	global_store_dwordx4 v[158:159], v[240:243], off offset:64
	s_nop 0
	v_mfma_f32_16x16x32_bf16 v[40:43], v[240:243], v[28:31], v[40:43]
	global_load_dwordx4 v[124:127], v[152:153], off offset:640 nt
	global_load_dwordx4 v[128:131], v[152:153], off offset:656 nt
	s_waitcnt vmcnt(32)
	v_cvt_pk_bf16_f32 v236, v132, v133
	v_cvt_pk_bf16_f32 v237, v134, v135
	v_cvt_pk_bf16_f32 v238, v136, v137
	v_cvt_pk_bf16_f32 v239, v138, v139
	global_store_dwordx4 v[158:159], v[236:239], off offset:128
	s_nop 0
	v_mfma_f32_16x16x32_bf16 v[40:43], v[236:239], v[24:27], v[40:43]
	global_load_dwordx4 v[132:135], v[152:153], off offset:768 nt
	global_load_dwordx4 v[136:139], v[152:153], off offset:784 nt
	s_waitcnt vmcnt(33)
	v_cvt_pk_bf16_f32 v240, v140, v141
	v_cvt_pk_bf16_f32 v241, v142, v143
	v_cvt_pk_bf16_f32 v242, v144, v145
	v_cvt_pk_bf16_f32 v243, v146, v147
	global_store_dwordx4 v[158:159], v[240:243], off offset:192
	s_nop 0
	v_mfma_f32_16x16x32_bf16 v[40:43], v[240:243], v[20:23], v[40:43]
	global_load_dwordx4 v[140:143], v[152:153], off offset:896 nt
	global_load_dwordx4 v[144:147], v[152:153], off offset:912 nt
	s_waitcnt vmcnt(33)
	v_cvt_pk_bf16_f32 v236, v52, v53
	v_cvt_pk_bf16_f32 v237, v54, v55
	v_cvt_pk_bf16_f32 v238, v56, v57
	v_cvt_pk_bf16_f32 v239, v58, v59
	global_store_dwordx4 v[158:159], v[236:239], off offset:256
	s_nop 0
	v_mfma_f32_16x16x32_bf16 v[40:43], v[236:239], v[16:19], v[40:43]
	global_load_dwordx4 v[52:55], v[154:155], off nt
	global_load_dwordx4 v[56:59], v[154:155], off offset:16 nt
	s_waitcnt vmcnt(33)
	v_cvt_pk_bf16_f32 v240, v60, v61
	v_cvt_pk_bf16_f32 v241, v62, v63
	v_cvt_pk_bf16_f32 v242, v64, v65
	v_cvt_pk_bf16_f32 v243, v66, v67
	global_store_dwordx4 v[158:159], v[240:243], off offset:320
	s_nop 0
	v_mfma_f32_16x16x32_bf16 v[40:43], v[240:243], v[12:15], v[40:43]
	global_load_dwordx4 v[60:63], v[154:155], off offset:128 nt
	global_load_dwordx4 v[64:67], v[154:155], off offset:144 nt
	s_waitcnt vmcnt(33)
; __device__ __forceinline__ unsigned cvt_pk_bf16(float lo, float hi) { const f32x2v v = {lo, hi}; const b16x2v r = __builtin_convertvector(v, b16x2v); return __builtin_bit_cast(unsigned, r); }
; __device__ __forceinline__ f32x4 mfma16(bf16x8 a, bf16x8 b, f32x4 c) { return __builtin_amdgcn_mfma_f32_16x16x32_bf16(a, b, c, 0, 0, 0); }
; __device__ void prep_phase(const Params& p, unsigned char* smem_g) {
;     ...
;         for (int mt = 0; mt < 4; ++mt) {
;             acc[mt] = (f32x4){0.f, 0.f, 0.f, 0.f};
; #pragma unroll
;             for (int ks = 0; ks < 8; ++ks) {
;                 const size_t off = (size_t)(t0 + 16 * ((mt + mrot) & 3) + idx) * DM + 256 * wk + 32 * ks + 8 * g;
;                 const f32x4 a = *(const f32x4*)(p.x + off), b = *(const f32x4*)(p.x + off + 4);
;                 u32x4 w; w.x = cvt_pk_bf16(a[0], a[1]); w.y = cvt_pk_bf16(a[2], a[3]); w.z = cvt_pk_bf16(b[0], b[1]); w.w = cvt_pk_bf16(b[2], b[3]);
;                 *(u32x4*)(xb + off) = w;
;                 acc[mt] = mfma16(__builtin_bit_cast(bf16x8, w), bfr[ks], acc[mt]);
;             }
;         }
; #pragma unroll
;         for (int mt = 0; mt < 4; ++mt)
; #pragma unroll
;             for (int r = 0; r < 4; ++r) red[(wid * 64 + 16 * ((mt + mrot) & 3) + 4 * g + r) * 16 + idx] = acc[mt][r];
;         __syncthreads();
	v_cvt_pk_bf16_f32 v236, v68, v69
	v_cvt_pk_bf16_f32 v237, v70, v71
	v_cvt_pk_bf16_f32 v238, v72, v73
	v_cvt_pk_bf16_f32 v239, v74, v75
	global_store_dwordx4 v[158:159], v[236:239], off offset:384
	s_nop 0
	v_mfma_f32_16x16x32_bf16 v[40:43], v[236:239], v[8:11], v[40:43]
	global_load_dwordx4 v[68:71], v[154:155], off offset:256 nt
	global_load_dwordx4 v[72:75], v[154:155], off offset:272 nt
	s_waitcnt vmcnt(33)
	v_cvt_pk_bf16_f32 v240, v76, v77
	v_cvt_pk_bf16_f32 v241, v78, v79
	v_cvt_pk_bf16_f32 v242, v80, v81
	v_cvt_pk_bf16_f32 v243, v82, v83
	global_store_dwordx4 v[158:159], v[240:243], off offset:448
	s_nop 0
	v_mfma_f32_16x16x32_bf16 v[40:43], v[240:243], v[4:7], v[40:43]
	global_load_dwordx4 v[76:79], v[154:155], off offset:384 nt
	global_load_dwordx4 v[80:83], v[154:155], off offset:400 nt
	s_waitcnt vmcnt(33)
	v_cvt_pk_bf16_f32 v236, v84, v85
	v_cvt_pk_bf16_f32 v237, v86, v87
	v_cvt_pk_bf16_f32 v238, v88, v89
	v_cvt_pk_bf16_f32 v239, v90, v91
	global_store_dwordx4 v[160:161], v[236:239], off
	s_nop 0
	v_mfma_f32_16x16x32_bf16 v[44:47], v[236:239], v[32:35], 0
	global_load_dwordx4 v[84:87], v[154:155], off offset:512 nt
	global_load_dwordx4 v[88:91], v[154:155], off offset:528 nt
	s_waitcnt vmcnt(33)
	v_cvt_pk_bf16_f32 v240, v92, v93
	v_cvt_pk_bf16_f32 v241, v94, v95
	v_cvt_pk_bf16_f32 v242, v96, v97
	v_cvt_pk_bf16_f32 v243, v98, v99
	global_store_dwordx4 v[160:161], v[240:243], off offset:64
	s_nop 0
	v_mfma_f32_16x16x32_bf16 v[44:47], v[240:243], v[28:31], v[44:47]
	global_load_dwordx4 v[92:95], v[154:155], off offset:640 nt
	global_load_dwordx4 v[96:99], v[154:155], off offset:656 nt
	s_waitcnt vmcnt(33)
	v_cvt_pk_bf16_f32 v236, v100, v101
	v_cvt_pk_bf16_f32 v237, v102, v103
	v_cvt_pk_bf16_f32 v238, v104, v105
	v_cvt_pk_bf16_f32 v239, v106, v107
	global_store_dwordx4 v[160:161], v[236:239], off offset:128
	s_nop 0
	v_mfma_f32_16x16x32_bf16 v[44:47], v[236:239], v[24:27], v[44:47]
	global_load_dwordx4 v[100:103], v[154:155], off offset:768 nt
	global_load_dwordx4 v[104:107], v[154:155], off offset:784 nt
	s_waitcnt vmcnt(33)
	v_cvt_pk_bf16_f32 v240, v108, v109
	v_cvt_pk_bf16_f32 v241, v110, v111
	v_cvt_pk_bf16_f32 v242, v112, v113
	v_cvt_pk_bf16_f32 v243, v114, v115
	global_store_dwordx4 v[160:161], v[240:243], off offset:192
	s_nop 0
	v_mfma_f32_16x16x32_bf16 v[44:47], v[240:243], v[20:23], v[44:47]
	global_load_dwordx4 v[108:111], v[154:155], off offset:896 nt
	global_load_dwordx4 v[112:115], v[154:155], off offset:912 nt
	s_waitcnt vmcnt(33)
	v_cvt_pk_bf16_f32 v236, v116, v117
	v_cvt_pk_bf16_f32 v237, v118, v119
	v_cvt_pk_bf16_f32 v238, v120, v121
	v_cvt_pk_bf16_f32 v239, v122, v123
	global_store_dwordx4 v[160:161], v[236:239], off offset:256
	s_nop 0
	v_mfma_f32_16x16x32_bf16 v[44:47], v[236:239], v[16:19], v[44:47]
	s_waitcnt vmcnt(31)
	v_cvt_pk_bf16_f32 v240, v124, v125
	v_cvt_pk_bf16_f32 v241, v126, v127
	v_cvt_pk_bf16_f32 v242, v128, v129
	v_cvt_pk_bf16_f32 v243, v130, v131
	global_store_dwordx4 v[160:161], v[240:243], off offset:320
	s_nop 0
	v_mfma_f32_16x16x32_bf16 v[44:47], v[240:243], v[12:15], v[44:47]
	s_waitcnt vmcnt(29)
	v_cvt_pk_bf16_f32 v236, v132, v133
	v_cvt_pk_bf16_f32 v237, v134, v135
	v_cvt_pk_bf16_f32 v238, v136, v137
	v_cvt_pk_bf16_f32 v239, v138, v139
	global_store_dwordx4 v[160:161], v[236:239], off offset:384
	s_nop 0
	v_mfma_f32_16x16x32_bf16 v[44:47], v[236:239], v[8:11], v[44:47]
	s_waitcnt vmcnt(27)
	v_cvt_pk_bf16_f32 v240, v140, v141
	v_cvt_pk_bf16_f32 v241, v142, v143
	v_cvt_pk_bf16_f32 v242, v144, v145
	v_cvt_pk_bf16_f32 v243, v146, v147
	global_store_dwordx4 v[160:161], v[240:243], off offset:448
	s_nop 0
	v_mfma_f32_16x16x32_bf16 v[44:47], v[240:243], v[4:7], v[44:47]
	s_waitcnt vmcnt(25)
	v_cvt_pk_bf16_f32 v236, v52, v53
	v_cvt_pk_bf16_f32 v237, v54, v55
	v_cvt_pk_bf16_f32 v238, v56, v57
	v_cvt_pk_bf16_f32 v239, v58, v59
	global_store_dwordx4 v[162:163], v[236:239], off
	s_nop 0
	v_mfma_f32_16x16x32_bf16 v[164:167], v[236:239], v[32:35], 0
	s_waitcnt vmcnt(23)
	v_cvt_pk_bf16_f32 v240, v60, v61
	v_cvt_pk_bf16_f32 v241, v62, v63
	v_cvt_pk_bf16_f32 v242, v64, v65
	v_cvt_pk_bf16_f32 v243, v66, v67
	global_store_dwordx4 v[162:163], v[240:243], off offset:64
	s_nop 0
	v_mfma_f32_16x16x32_bf16 v[164:167], v[240:243], v[28:31], v[164:167]
	s_waitcnt vmcnt(21)
	v_cvt_pk_bf16_f32 v236, v68, v69
	v_cvt_pk_bf16_f32 v237, v70, v71
	v_cvt_pk_bf16_f32 v238, v72, v73
	v_cvt_pk_bf16_f32 v239, v74, v75
	global_store_dwordx4 v[162:163], v[236:239], off offset:128
	s_nop 0
	v_mfma_f32_16x16x32_bf16 v[164:167], v[236:239], v[24:27], v[164:167]
	s_waitcnt vmcnt(19)
	v_cvt_pk_bf16_f32 v240, v76, v77
	v_cvt_pk_bf16_f32 v241, v78, v79
	v_cvt_pk_bf16_f32 v242, v80, v81
	v_cvt_pk_bf16_f32 v243, v82, v83
	global_store_dwordx4 v[162:163], v[240:243], off offset:192
	s_nop 0
	v_mfma_f32_16x16x32_bf16 v[164:167], v[240:243], v[20:23], v[164:167]
	s_waitcnt vmcnt(17)
	v_cvt_pk_bf16_f32 v236, v84, v85
	v_cvt_pk_bf16_f32 v237, v86, v87
	v_cvt_pk_bf16_f32 v238, v88, v89
	v_cvt_pk_bf16_f32 v239, v90, v91
	global_store_dwordx4 v[162:163], v[236:239], off offset:256
	s_nop 0
	v_mfma_f32_16x16x32_bf16 v[164:167], v[236:239], v[16:19], v[164:167]
	s_waitcnt vmcnt(15)
	v_cvt_pk_bf16_f32 v240, v92, v93
	v_cvt_pk_bf16_f32 v241, v94, v95
	v_cvt_pk_bf16_f32 v242, v96, v97
	v_cvt_pk_bf16_f32 v243, v98, v99
	global_store_dwordx4 v[162:163], v[240:243], off offset:320
	s_nop 0
	v_mfma_f32_16x16x32_bf16 v[164:167], v[240:243], v[12:15], v[164:167]
	s_waitcnt vmcnt(13)
	v_cvt_pk_bf16_f32 v236, v100, v101
	v_cvt_pk_bf16_f32 v237, v102, v103
	v_cvt_pk_bf16_f32 v238, v104, v105
	v_cvt_pk_bf16_f32 v239, v106, v107
	global_store_dwordx4 v[162:163], v[236:239], off offset:384
	s_nop 0
	v_mfma_f32_16x16x32_bf16 v[164:167], v[236:239], v[8:11], v[164:167]
	s_waitcnt vmcnt(11)
	v_cvt_pk_bf16_f32 v240, v108, v109
	v_cvt_pk_bf16_f32 v241, v110, v111
	v_cvt_pk_bf16_f32 v242, v112, v113
	v_cvt_pk_bf16_f32 v243, v114, v115
	global_store_dwordx4 v[162:163], v[240:243], off offset:448
	s_nop 0
	v_mfma_f32_16x16x32_bf16 v[164:167], v[240:243], v[4:7], v[164:167]
	v_mov_b32_e32 v21, 0
	s_nop 4
	ds_write2_b32 v2, v36, v37 offset1:16
	ds_write2_b32 v2, v38, v39 offset0:32 offset1:48
	ds_write2_b32 v232, v40, v41 offset1:16
	ds_write2_b32 v232, v42, v43 offset0:32 offset1:48
	ds_write2_b32 v233, v44, v45 offset1:16
	ds_write2_b32 v233, v46, v47 offset0:32 offset1:48
	s_nop 1
	ds_write2_b32 v235, v164, v165 offset1:16
	ds_write2_b32 v235, v166, v167 offset0:32 offset1:48
	s_waitcnt lgkmcnt(0)
	s_barrier
; __device__ void prep_phase(const Params& p, unsigned char* smem_g) {
;     ...
;         __syncthreads();
;         { const int tok = tid >> 3, c2 = (tid & 7) * 2; float s0 = 0.f, s1 = 0.f;
; #pragma unroll
;           for (int w = 0; w < 8; ++w) { s0 += red[(w * 64 + tok) * 16 + c2]; s1 += red[(w * 64 + tok) * 16 + c2 + 1]; }
;           glrs[tok * 16 + c2] = s0; glrs[tok * 16 + c2 + 1] = s1; }
;         __syncthreads();
;         { const int c = tid; float w2c[16];
; #pragma unroll
;           for (int r = 0; r < 16; ++r) w2c[r] = p.gate_w2[r * 512 + c];
;           const float bias = p.gate_b[c]; float b2 = 0.f;
	ds_read2st64_b64 v[4:7], v1 offset1:8
	s_waitcnt lgkmcnt(0)
	v_pk_add_f32 v[4:5], v[4:5], 0 op_sel_hi:[1,0]
	s_nop 0
	v_pk_add_f32 v[8:9], v[4:5], v[6:7]
	ds_read2st64_b64 v[4:7], v1 offset0:16 offset1:24
	s_waitcnt lgkmcnt(0)
	v_pk_add_f32 v[4:5], v[8:9], v[4:5]
	s_nop 0
	v_pk_add_f32 v[8:9], v[4:5], v[6:7]
	ds_read2st64_b64 v[4:7], v1 offset0:32 offset1:40
	s_waitcnt lgkmcnt(0)
	v_pk_add_f32 v[4:5], v[8:9], v[4:5]
	s_nop 0
	v_pk_add_f32 v[8:9], v[4:5], v[6:7]
	ds_read2st64_b64 v[4:7], v1 offset0:48 offset1:56
	s_waitcnt lgkmcnt(0)
	v_pk_add_f32 v[4:5], v[8:9], v[4:5]
	s_nop 0
	v_pk_add_f32 v[4:5], v[4:5], v[6:7]
	ds_write_b64 v1, v[4:5] offset:32768
	s_waitcnt lgkmcnt(0)
	s_barrier
	global_load_dword v4, v[180:181], off
	global_load_dword v6, v[180:181], off offset:2048
	global_load_dword v8, v[182:183], off
	global_load_dword v10, v[186:187], off
	global_load_dword v5, v[188:189], off
	global_load_dword v7, v[190:191], off
	global_load_dword v9, v[192:193], off
	global_load_dword v11, v[194:195], off
	global_load_dword v12, v[196:197], off
	global_load_dword v14, v[198:199], off
	global_load_dword v16, v[200:201], off
	global_load_dword v18, v[202:203], off
	global_load_dword v13, v[204:205], off
	global_load_dword v15, v[206:207], off
	global_load_dword v17, v[208:209], off
	global_load_dword v19, v[210:211], off
	global_load_dword v20, v[184:185], off
	s_waitcnt vmcnt(0)

; __device__ __forceinline__ int opaque_tid() { int t = (int)threadIdx.x; asm volatile("" : "+v"(t)); return t; }
; __device__ __forceinline__ int wt_remap(int grp, int t) { return (grp == 2) ? (t < 768 ? t : t + 512) : t; }
; __device__ __forceinline__ void wt_load(const WtDesc& d, int tid, f32x4 (&v)[8]) {
;     const int r = tid >> 6, c4 = tid & 63; const int col = (c4 < 32) ? d.ns0 + 4 * c4 : d.ns1 + 4 * (c4 - 32);
; #pragma unroll
;     for (int i = 0; i < 8; ++i) v[i] = *(const f32x4*)(d.W + (size_t)(d.k0 + r + 8 * i) * d.ldw + col);
; }
; __device__ void wt_run(const Params& p, int grp, int first, int stride, int ntiles, unsigned char* smem_g) {
;     constexpr int LD = 260;
;     float* tile = (float*)smem_g;
;     const int tid = opaque_tid();
;     int tl = first;
;     if (tl >= ntiles) return;
;     const int dg = (grp == 2) ? 0 : grp;
;     WtDesc cur = wt_decode(p, dg, wt_remap(grp, tl)); f32x4 v[8];
;     wt_load(cur, tid, v);
;     for (;;) {
;         { const int r = tid >> 6, c4 = tid & 63;
; #pragma unroll
;           for (int i = 0; i < 8; ++i) *(f32x4*)(tile + (r + 8 * i) * LD + 4 * c4) = v[i]; }
;         const int nxt = tl + stride; const bool has = nxt < ntiles;
;         WtDesc nd = cur;
;         if (has) { nd = wt_decode(p, dg, wt_remap(grp, nxt)); wt_load(nd, tid, v); }
.LBB0_158:
	s_waitcnt vmcnt(0)
	v_and_b32_e32 v4, 63, v2
	v_lshlrev_b32_e32 v0, 2, v4
	v_add_u32_e32 v1, 0xffffff80, v0
	v_add_u32_e32 v5, s1, v0
	v_add_u32_e32 v6, s0, v1
	v_cmp_gt_u32_e64 s[0:1], 32, v4
	v_ashrrev_i32_e32 v36, 6, v2
	v_readlane_b32 s9, v252, 11
	v_cndmask_b32_e64 v4, v6, v5, s[0:1]
	v_ashrrev_i32_e32 v5, 31, v4
	v_add_u32_e32 v6, s9, v36
	v_mad_i64_i32 v[6:7], s[10:11], s4, v6, 0
	v_lshl_add_u64 v[6:7], v[6:7], 2, s[6:7]
	v_lshlrev_b64 v[28:29], 2, v[4:5]
	v_add_u32_e32 v37, 8, v36
	v_add_u32_e32 v38, 16, v36
	v_add_u32_e32 v39, 24, v36
	v_add_u32_e32 v40, 32, v36
	v_add_u32_e32 v41, 40, v36
	v_add_u32_e32 v42, 48, v36
	v_add_u32_e32 v43, 56, v36
	v_lshl_add_u64 v[4:5], v[6:7], 0, v[28:29]
	v_add_u32_e32 v6, s9, v37
	v_add_u32_e32 v12, s9, v38
	v_add_u32_e32 v14, s9, v39
	v_add_u32_e32 v20, s9, v40
	v_add_u32_e32 v22, s9, v41
	v_add_u32_e32 v30, s9, v42
	v_add_u32_e32 v32, s9, v43
	v_mad_i64_i32 v[6:7], s[10:11], s4, v6, 0
	v_mad_i64_i32 v[12:13], s[10:11], s4, v12, 0
	v_mad_i64_i32 v[14:15], s[10:11], s4, v14, 0
	v_mad_i64_i32 v[20:21], s[10:11], s4, v20, 0
	v_mad_i64_i32 v[22:23], s[10:11], s4, v22, 0
	v_mad_i64_i32 v[30:31], s[10:11], s4, v30, 0
	v_mad_i64_i32 v[32:33], s[4:5], s4, v32, 0
	v_lshl_add_u64 v[6:7], v[6:7], 2, s[6:7]
	v_lshl_add_u64 v[12:13], v[12:13], 2, s[6:7]
	v_lshl_add_u64 v[14:15], v[14:15], 2, s[6:7]
	v_lshl_add_u64 v[20:21], v[20:21], 2, s[6:7]
	v_lshl_add_u64 v[22:23], v[22:23], 2, s[6:7]
	v_lshl_add_u64 v[30:31], v[30:31], 2, s[6:7]
	v_lshl_add_u64 v[32:33], v[32:33], 2, s[6:7]
	v_lshl_add_u64 v[8:9], v[6:7], 0, v[28:29]
	v_lshl_add_u64 v[12:13], v[12:13], 0, v[28:29]
	v_lshl_add_u64 v[16:17], v[14:15], 0, v[28:29]
	v_lshl_add_u64 v[20:21], v[20:21], 0, v[28:29]
	v_lshl_add_u64 v[24:25], v[22:23], 0, v[28:29]
	v_lshl_add_u64 v[30:31], v[30:31], 0, v[28:29]
	v_lshl_add_u64 v[32:33], v[32:33], 0, v[28:29]
	global_load_dwordx4 v[4:7], v[4:5], off nt
	s_nop 0
	global_load_dwordx4 v[8:11], v[8:9], off nt
	s_nop 0
	global_load_dwordx4 v[12:15], v[12:13], off nt
	s_nop 0
	global_load_dwordx4 v[16:19], v[16:17], off nt
	s_nop 0
	global_load_dwordx4 v[20:23], v[20:21], off nt
	s_nop 0
	global_load_dwordx4 v[24:27], v[24:25], off nt
	s_nop 0
	global_load_dwordx4 v[28:31], v[30:31], off nt
	s_nop 0
	global_load_dwordx4 v[32:35], v[32:33], off nt
	v_readlane_b32 s4, v251, 8
	v_readlane_b32 s5, v251, 9
	s_load_dword s6, s[4:5], 0x0
	s_and_b32 s4, 0xffff, s8
	s_cmp_lg_u32 s4, 0
	s_cselect_b64 s[4:5], -1, 0
	v_lshlrev_b32_e32 v44, 4, v2
	s_cmp_lg_u64 s[4:5], 0
	v_and_b32_e32 v44, 0x3f0, v44
	s_waitcnt lgkmcnt(0)
	s_addc_u32 s15, s6, 0
	v_add_u32_e32 v45, 0, v44
	v_ashrrev_i32_e32 v44, 1, v2
	v_lshlrev_b32_e32 v2, 5, v2
	s_add_u32 s4, s92, s2
	v_and_b32_e32 v2, 32, v2
	s_movk_i32 s2, 0x410
	s_addc_u32 s5, s93, s3
	v_lshl_add_u32 v46, v44, 2, 0
	v_mul_lo_u32 v47, v36, s2
	v_mul_u32_u24_e32 v48, 0x410, v2
	v_add_u32_e32 v45, v45, v47
	v_lshlrev_b32_e32 v2, 1, v2
	v_add_u32_e32 v46, v46, v48
	s_mov_b32 s16, s34
	s_mov_b32 s18, s9
	s_mov_b64 s[6:7], s[4:5]
	s_mov_b32 s12, s17
	s_branch .LBB0_161
.LBB0_159:
	s_add_u32 s6, s92, s6
	s_addc_u32 s7, s93, s7
	s_lshl_b32 s13, s22, 6
	s_and_b32 s13, s13, 0x7c0
	v_add_u32_e32 v6, s13, v36
	v_add_u32_e32 v4, s24, v0
	v_add_u32_e32 v5, s23, v1
	v_ashrrev_i32_e32 v7, 31, v6
	v_cndmask_b32_e64 v4, v5, v4, s[0:1]
	v_mul_lo_u32 v8, s10, v7
	v_mul_lo_u32 v9, s11, v6
	v_mad_u64_u32 v[6:7], s[22:23], s10, v6, 0
	v_add_u32_e32 v12, s13, v38
	v_add_u32_e32 v20, s13, v40
	v_add_u32_e32 v30, s13, v42
	v_ashrrev_i32_e32 v5, 31, v4
	v_add3_u32 v7, v7, v8, v9
	v_ashrrev_i32_e32 v13, 31, v12
	v_ashrrev_i32_e32 v21, 31, v20
	v_ashrrev_i32_e32 v31, 31, v30
	v_lshl_add_u64 v[6:7], v[6:7], 2, s[8:9]
	v_lshlrev_b64 v[28:29], 2, v[4:5]
	v_mul_lo_u32 v14, s10, v13
	v_mul_lo_u32 v15, s11, v12
	v_mad_u64_u32 v[12:13], s[22:23], s10, v12, 0
	v_mul_lo_u32 v22, s10, v21
	v_mul_lo_u32 v23, s11, v20
	v_mad_u64_u32 v[20:21], s[22:23], s10, v20, 0
	v_mul_lo_u32 v32, s10, v31
	v_mul_lo_u32 v33, s11, v30
	v_mad_u64_u32 v[30:31], s[22:23], s10, v30, 0
	v_lshl_add_u64 v[4:5], v[6:7], 0, v[28:29]
	v_add_u32_e32 v6, s13, v37
	v_add3_u32 v13, v13, v14, v15
	v_add_u32_e32 v14, s13, v39
	v_add3_u32 v21, v21, v22, v23
	v_add_u32_e32 v22, s13, v41
	v_add3_u32 v31, v31, v32, v33
	v_add_u32_e32 v32, s13, v43
	v_ashrrev_i32_e32 v7, 31, v6
	v_ashrrev_i32_e32 v15, 31, v14
	v_ashrrev_i32_e32 v23, 31, v22
	v_ashrrev_i32_e32 v33, 31, v32
	v_mul_lo_u32 v8, s10, v7
	v_mul_lo_u32 v9, s11, v6
	v_mad_u64_u32 v[6:7], s[22:23], s10, v6, 0
	v_mul_lo_u32 v16, s10, v15
	v_mul_lo_u32 v17, s11, v14
	v_mad_u64_u32 v[14:15], s[22:23], s10, v14, 0
	v_mul_lo_u32 v24, s10, v23
	v_mul_lo_u32 v25, s11, v22
	v_mad_u64_u32 v[22:23], s[22:23], s10, v22, 0
	v_mul_lo_u32 v34, s10, v33
	v_mul_lo_u32 v35, s11, v32
	v_mad_u64_u32 v[32:33], s[10:11], s10, v32, 0
	v_add3_u32 v7, v7, v8, v9
	v_add3_u32 v15, v15, v16, v17
	v_add3_u32 v23, v23, v24, v25
	v_add3_u32 v33, v33, v34, v35
	v_lshl_add_u64 v[6:7], v[6:7], 2, s[8:9]
	v_lshl_add_u64 v[12:13], v[12:13], 2, s[8:9]
	v_lshl_add_u64 v[14:15], v[14:15], 2, s[8:9]
	v_lshl_add_u64 v[20:21], v[20:21], 2, s[8:9]
	v_lshl_add_u64 v[22:23], v[22:23], 2, s[8:9]
	v_lshl_add_u64 v[30:31], v[30:31], 2, s[8:9]
	v_lshl_add_u64 v[32:33], v[32:33], 2, s[8:9]
	v_lshl_add_u64 v[8:9], v[6:7], 0, v[28:29]
	v_lshl_add_u64 v[12:13], v[12:13], 0, v[28:29]
	v_lshl_add_u64 v[16:17], v[14:15], 0, v[28:29]
	v_lshl_add_u64 v[20:21], v[20:21], 0, v[28:29]
	v_lshl_add_u64 v[24:25], v[22:23], 0, v[28:29]
	v_lshl_add_u64 v[30:31], v[30:31], 0, v[28:29]
	v_lshl_add_u64 v[32:33], v[32:33], 0, v[28:29]
	global_load_dwordx4 v[4:7], v[4:5], off nt
	s_nop 0
	global_load_dwordx4 v[8:11], v[8:9], off nt
	s_nop 0
	global_load_dwordx4 v[12:15], v[12:13], off nt
	s_nop 0
	global_load_dwordx4 v[16:19], v[16:17], off nt
	s_nop 0
	global_load_dwordx4 v[20:23], v[20:21], off nt
	s_nop 0
	global_load_dwordx4 v[24:27], v[24:25], off nt
	s_nop 0
	global_load_dwordx4 v[28:31], v[30:31], off nt
	s_nop 0
	global_load_dwordx4 v[32:35], v[32:33], off nt
	v_readlane_b32 s24, v254, 17
	v_readlane_b32 s25, v254, 18

; __device__ __forceinline__ int opaque_tid() { int t = (int)threadIdx.x; asm volatile("" : "+v"(t)); return t; }
; __device__ __forceinline__ int wt_remap(int grp, int t) { return (grp == 2) ? (t < 768 ? t : t + 512) : t; }
; __device__ __forceinline__ void wt_load(const WtDesc& d, int tid, f32x4 (&v)[8]) {
;     const int r = tid >> 6, c4 = tid & 63; const int col = (c4 < 32) ? d.ns0 + 4 * c4 : d.ns1 + 4 * (c4 - 32);
; #pragma unroll
;     for (int i = 0; i < 8; ++i) v[i] = *(const f32x4*)(d.W + (size_t)(d.k0 + r + 8 * i) * d.ldw + col);
; }
; __device__ void wt_run(const Params& p, int grp, int first, int stride, int ntiles, unsigned char* smem_g) {
;     constexpr int LD = 260;
;     float* tile = (float*)smem_g;
;     const int tid = opaque_tid();
;     int tl = first;
;     if (tl >= ntiles) return;
;     const int dg = (grp == 2) ? 0 : grp;
;     WtDesc cur = wt_decode(p, dg, wt_remap(grp, tl)); f32x4 v[8];
;     wt_load(cur, tid, v);
;     for (;;) {
;         { const int r = tid >> 6, c4 = tid & 63;
; #pragma unroll
;           for (int i = 0; i < 8; ++i) *(f32x4*)(tile + (r + 8 * i) * LD + 4 * c4) = v[i]; }
.LBB0_398:
	v_readlane_b32 s0, v254, 37
	v_readlane_b32 s2, v254, 42
	v_readlane_b32 s1, v254, 38
	v_readlane_b32 s3, v254, 43
	s_and_b64 s[0:1], s[0:1], s[2:3]
	s_andn2_b64 vcc, exec, s[0:1]
	s_cbranch_vccnz .LBB0_409
	v_readlane_b32 s0, v252, 18
	v_readlane_b32 s1, v252, 19
	v_mov_b32_e32 v0, v212
	s_andn2_b64 vcc, exec, s[0:1]
	s_cbranch_vccnz .LBB0_409
	v_and_b32_e32 v1, 63, v0
	s_waitcnt vmcnt(0)
	v_lshlrev_b32_e32 v36, 2, v1
	v_readlane_b32 s22, v252, 21
	v_add_u32_e32 v37, 0xffffff80, v36
	v_readlane_b32 s0, v252, 22
	v_ashrrev_i32_e32 v38, 6, v0
	v_or_b32_e32 v2, s22, v36
	v_add_u32_e32 v4, s0, v37
	v_cmp_gt_u32_e64 s[0:1], 32, v1
	v_readlane_b32 s2, v252, 20
	v_add_u32_e32 v39, 8, v38
	v_add_u32_e32 v40, 16, v38
	v_add_u32_e32 v41, 24, v38
	v_add_u32_e32 v42, 32, v38
	v_add_u32_e32 v43, 40, v38
	v_add_u32_e32 v44, 48, v38
	v_add_u32_e32 v45, 56, v38
	v_cndmask_b32_e64 v2, v4, v2, s[0:1]
	v_add_u32_e32 v4, s2, v38
	v_add_u32_e32 v6, s2, v39
	v_add_u32_e32 v12, s2, v40
	v_add_u32_e32 v14, s2, v41
	v_add_u32_e32 v20, s2, v42
	v_add_u32_e32 v22, s2, v43
	v_add_u32_e32 v30, s2, v44
	v_add_u32_e32 v32, s2, v45
	v_ashrrev_i32_e32 v5, 31, v4
	v_readlane_b32 s4, v251, 0
	v_ashrrev_i32_e32 v7, 31, v6
	v_ashrrev_i32_e32 v13, 31, v12
	v_ashrrev_i32_e32 v15, 31, v14
	v_ashrrev_i32_e32 v21, 31, v20
	v_ashrrev_i32_e32 v23, 31, v22
	v_ashrrev_i32_e32 v31, 31, v30
	v_ashrrev_i32_e32 v33, 31, v32
	v_lshlrev_b64 v[4:5], 13, v[4:5]
	v_readlane_b32 s8, v251, 4
	v_readlane_b32 s9, v251, 5
	v_lshlrev_b64 v[6:7], 13, v[6:7]
	v_lshlrev_b64 v[12:13], 13, v[12:13]
	v_lshlrev_b64 v[14:15], 13, v[14:15]
	v_lshlrev_b64 v[20:21], 13, v[20:21]
	v_lshlrev_b64 v[22:23], 13, v[22:23]
	v_lshlrev_b64 v[30:31], 13, v[30:31]
	v_lshlrev_b64 v[32:33], 13, v[32:33]
	v_lshl_add_u64 v[4:5], s[8:9], 0, v[4:5]
	v_lshlrev_b64 v[28:29], 2, v[2:3]
	v_lshl_add_u64 v[6:7], s[8:9], 0, v[6:7]
	v_lshl_add_u64 v[12:13], s[8:9], 0, v[12:13]
	v_lshl_add_u64 v[14:15], s[8:9], 0, v[14:15]
	v_lshl_add_u64 v[20:21], s[8:9], 0, v[20:21]
	v_lshl_add_u64 v[22:23], s[8:9], 0, v[22:23]
	v_lshl_add_u64 v[30:31], s[8:9], 0, v[30:31]
	v_lshl_add_u64 v[32:33], s[8:9], 0, v[32:33]
	v_lshl_add_u64 v[4:5], v[4:5], 0, v[28:29]
	v_lshl_add_u64 v[8:9], v[6:7], 0, v[28:29]
	v_lshl_add_u64 v[12:13], v[12:13], 0, v[28:29]
	v_lshl_add_u64 v[16:17], v[14:15], 0, v[28:29]
	v_lshl_add_u64 v[20:21], v[20:21], 0, v[28:29]
	v_lshl_add_u64 v[24:25], v[22:23], 0, v[28:29]
	v_lshl_add_u64 v[30:31], v[30:31], 0, v[28:29]
	v_lshl_add_u64 v[32:33], v[32:33], 0, v[28:29]
	global_load_dwordx4 v[4:7], v[4:5], off nt
	s_nop 0
	global_load_dwordx4 v[8:11], v[8:9], off nt
	s_nop 0
	global_load_dwordx4 v[12:15], v[12:13], off nt
	s_nop 0
	global_load_dwordx4 v[16:19], v[16:17], off nt
	s_nop 0
	global_load_dwordx4 v[20:23], v[20:21], off nt
	s_nop 0
	global_load_dwordx4 v[24:27], v[24:25], off nt
	s_nop 0
	global_load_dwordx4 v[28:31], v[30:31], off nt
	s_nop 0
	global_load_dwordx4 v[32:35], v[32:33], off nt
	v_lshlrev_b32_e32 v1, 4, v0
	v_ashrrev_i32_e32 v46, 1, v0
	v_lshlrev_b32_e32 v0, 5, v0
	v_and_b32_e32 v1, 0x3f0, v1
	v_and_b32_e32 v0, 32, v0
	s_movk_i32 s3, 0x410
	v_readlane_b32 s5, v251, 1
	v_readlane_b32 s10, v251, 6
	v_readlane_b32 s11, v251, 7
	v_add_u32_e32 v1, 0, v1
	v_lshl_add_u32 v2, v46, 2, 0
	v_mul_lo_u32 v47, v38, s3
	v_mul_u32_u24_e32 v48, 0x410, v0
	s_movk_i32 s17, 0x1580
	v_add_u32_e32 v47, v1, v47
	v_lshlrev_b32_e32 v0, 1, v0
	v_add_u32_e32 v48, v2, v48
	v_readlane_b32 s10, v254, 0
	v_readlane_b32 s11, v253, 63
	s_mov_b32 s18, s2
	s_mov_b64 s[4:5], s[66:67]
	s_mov_b64 s[2:3], s[66:67]
	s_mov_b32 s13, s17
	s_mov_b32 s16, s22
	v_readlane_b32 s6, v251, 2
	v_readlane_b32 s7, v251, 3
	s_branch .LBB0_404

; __device__ __forceinline__ int opaque_tid() { int t = (int)threadIdx.x; asm volatile("" : "+v"(t)); return t; }
; __device__ __forceinline__ int wt_remap(int grp, int t) { return (grp == 2) ? (t < 768 ? t : t + 512) : t; }
; __device__ __forceinline__ void wt_load(const WtDesc& d, int tid, f32x4 (&v)[8]) {
;     const int r = tid >> 6, c4 = tid & 63; const int col = (c4 < 32) ? d.ns0 + 4 * c4 : d.ns1 + 4 * (c4 - 32);
; #pragma unroll
;     for (int i = 0; i < 8; ++i) v[i] = *(const f32x4*)(d.W + (size_t)(d.k0 + r + 8 * i) * d.ldw + col);
; }
; __device__ void wt_run(const Params& p, int grp, int first, int stride, int ntiles, unsigned char* smem_g) {
;     constexpr int LD = 260;
;     float* tile = (float*)smem_g;
;     const int tid = opaque_tid();
;     int tl = first;
;     if (tl >= ntiles) return;
;     const int dg = (grp == 2) ? 0 : grp;
;     WtDesc cur = wt_decode(p, dg, wt_remap(grp, tl)); f32x4 v[8];
;     wt_load(cur, tid, v);
;     for (;;) {
;         { const int r = tid >> 6, c4 = tid & 63;
; #pragma unroll
;           for (int i = 0; i < 8; ++i) *(f32x4*)(tile + (r + 8 * i) * LD + 4 * c4) = v[i]; }
;         const int nxt = tl + stride; const bool has = nxt < ntiles;
;         WtDesc nd = cur;
;         if (has) { nd = wt_decode(p, dg, wt_remap(grp, nxt)); wt_load(nd, tid, v); }
.LBB0_402:
	v_add_u32_e32 v1, s23, v36
	v_add_u32_e32 v2, s24, v37
	v_cndmask_b32_e64 v2, v2, v1, s[0:1]
	v_add_u32_e32 v1, s15, v38
	v_mad_i64_i32 v[4:5], s[24:25], s8, v1, 0
	v_add_u32_e32 v1, s15, v39
	v_mad_i64_i32 v[6:7], s[24:25], s8, v1, 0
	v_add_u32_e32 v1, s15, v40
	v_mad_i64_i32 v[12:13], s[24:25], s8, v1, 0
	v_add_u32_e32 v1, s15, v41
	v_mad_i64_i32 v[14:15], s[24:25], s8, v1, 0
	v_add_u32_e32 v1, s15, v42
	v_mad_i64_i32 v[20:21], s[24:25], s8, v1, 0
	v_add_u32_e32 v1, s15, v43
	v_mad_i64_i32 v[22:23], s[24:25], s8, v1, 0
	v_add_u32_e32 v1, s15, v44
	v_mad_i64_i32 v[30:31], s[24:25], s8, v1, 0
	v_add_u32_e32 v1, s15, v45
	v_mad_i64_i32 v[32:33], s[8:9], s8, v1, 0
	v_lshl_add_u64 v[4:5], v[4:5], 2, s[6:7]
	v_lshlrev_b64 v[28:29], 2, v[2:3]
	v_lshl_add_u64 v[6:7], v[6:7], 2, s[6:7]
	v_lshl_add_u64 v[12:13], v[12:13], 2, s[6:7]
	v_lshl_add_u64 v[14:15], v[14:15], 2, s[6:7]
	v_lshl_add_u64 v[20:21], v[20:21], 2, s[6:7]
	v_lshl_add_u64 v[22:23], v[22:23], 2, s[6:7]
	v_lshl_add_u64 v[30:31], v[30:31], 2, s[6:7]
	v_lshl_add_u64 v[32:33], v[32:33], 2, s[6:7]
	v_lshl_add_u64 v[4:5], v[4:5], 0, v[28:29]
	v_lshl_add_u64 v[8:9], v[6:7], 0, v[28:29]
	v_lshl_add_u64 v[12:13], v[12:13], 0, v[28:29]
	v_lshl_add_u64 v[16:17], v[14:15], 0, v[28:29]
	v_lshl_add_u64 v[20:21], v[20:21], 0, v[28:29]
	v_lshl_add_u64 v[24:25], v[22:23], 0, v[28:29]
	v_lshl_add_u64 v[30:31], v[30:31], 0, v[28:29]
	v_lshl_add_u64 v[32:33], v[32:33], 0, v[28:29]
	global_load_dwordx4 v[4:7], v[4:5], off nt
	s_nop 0
	global_load_dwordx4 v[8:11], v[8:9], off nt
	s_nop 0
	global_load_dwordx4 v[12:15], v[12:13], off nt
	s_nop 0
	global_load_dwordx4 v[16:19], v[16:17], off nt
	s_nop 0
	global_load_dwordx4 v[20:23], v[20:21], off nt
	s_nop 0
	global_load_dwordx4 v[24:27], v[24:25], off nt
	s_nop 0
	global_load_dwordx4 v[28:31], v[30:31], off nt
	s_nop 0
	global_load_dwordx4 v[32:35], v[32:33], off nt
	v_readlane_b32 s24, v254, 17
	v_readlane_b32 s38, v254, 19
	v_readlane_b32 s25, v254, 18

; __device__ __forceinline__ unsigned cvt_pk_bf16(float lo, float hi) { const f32x2v v = {lo, hi}; const b16x2v r = __builtin_convertvector(v, b16x2v); return __builtin_bit_cast(unsigned, r); }
; __device__ void wt_one(const Params& p, int grp, int tl, unsigned char* smem_g) {
;     ...
;     const WtDesc cur = wt_decode(p, grp, tl); f32x4 v[8];
;     wt_load(cur, tid, v);
;     { const int r = tid >> 6, c4 = tid & 63;
; #pragma unroll
;       for (int i = 0; i < 8; ++i) *(f32x4*)(tile + (r + 8 * i) * LD + 4 * c4) = v[i]; }
;     __syncthreads();
;     { const int n = tid >> 1, kh = tid & 1;
; #pragma unroll
;       for (int q = 0; q < 4; ++q) {
;           float e[8];
; #pragma unroll
;           for (int j = 0; j < 8; ++j) e[j] = tile[(32 * kh + 8 * q + j) * LD + n];
;           u32x4 w; w.x = cvt_pk_bf16(e[0], e[1]); w.y = cvt_pk_bf16(e[2], e[3]); w.z = cvt_pk_bf16(e[4], e[5]); w.w = cvt_pk_bf16(e[6], e[7]);
;           *(u32x4*)(cur.Bt + (size_t)(cur.n0dst + n) * cur.K + cur.k0 + 32 * kh + 8 * q) = w;
;       } }
;     __syncthreads();
.LBB0_460:
	v_and_b32_e32 v1, 63, v0
	s_add_u32 s6, s92, s6
	v_lshlrev_b32_e32 v2, 2, v1
	s_addc_u32 s7, s93, s7
	s_lshl_b32 s9, s10, 6
	v_add_u32_e32 v4, s13, v2
	v_add_u32_e32 v2, s12, v2
	s_and_b32 s9, s9, 0x7c0
	v_add_u32_e32 v2, 0xffffff80, v2
	v_cmp_gt_u32_e32 vcc, 32, v1
	v_ashrrev_i32_e32 v1, 6, v0
	s_lshl_b32 s18, s9, 1
	v_cndmask_b32_e32 v4, v2, v4, vcc
	v_add_u32_e32 v2, s9, v1
	v_ashrrev_i32_e32 v6, 31, v2
	v_mul_lo_u32 v8, s4, v6
	v_mul_lo_u32 v9, s5, v2
	v_mad_u64_u32 v[6:7], s[10:11], s4, v2, 0
	v_add_u32_e32 v12, 16, v2
	v_add_u32_e32 v20, 32, v2
	v_ashrrev_i32_e32 v5, 31, v4
	v_add3_u32 v7, v7, v8, v9
	v_ashrrev_i32_e32 v13, 31, v12
	v_ashrrev_i32_e32 v21, 31, v20
	v_add_u32_e32 v30, 48, v2
	v_lshl_add_u64 v[6:7], v[6:7], 2, s[0:1]
	v_lshlrev_b64 v[28:29], 2, v[4:5]
	v_mul_lo_u32 v14, s4, v13
	v_mul_lo_u32 v15, s5, v12
	v_mad_u64_u32 v[12:13], s[10:11], s4, v12, 0
	v_mul_lo_u32 v22, s4, v21
	v_mul_lo_u32 v23, s5, v20
	v_mad_u64_u32 v[20:21], s[10:11], s4, v20, 0
	v_ashrrev_i32_e32 v31, 31, v30
	v_lshl_add_u64 v[4:5], v[6:7], 0, v[28:29]
	v_add_u32_e32 v6, 8, v2
	v_add3_u32 v13, v13, v14, v15
	v_add_u32_e32 v14, 24, v2
	v_add3_u32 v21, v21, v22, v23
	v_add_u32_e32 v22, 40, v2
	v_mul_lo_u32 v32, s4, v31
	v_mul_lo_u32 v33, s5, v30
	v_mad_u64_u32 v[30:31], s[10:11], s4, v30, 0
	v_add_u32_e32 v2, 56, v2
	v_ashrrev_i32_e32 v7, 31, v6
	v_ashrrev_i32_e32 v15, 31, v14
	v_ashrrev_i32_e32 v23, 31, v22
	v_add3_u32 v31, v31, v32, v33
	v_ashrrev_i32_e32 v32, 31, v2
	v_mul_lo_u32 v8, s4, v7
	v_mul_lo_u32 v9, s5, v6
	v_mad_u64_u32 v[6:7], s[10:11], s4, v6, 0
	v_mul_lo_u32 v16, s4, v15
	v_mul_lo_u32 v17, s5, v14
	v_mad_u64_u32 v[14:15], s[10:11], s4, v14, 0
	v_mul_lo_u32 v24, s4, v23
	v_mul_lo_u32 v25, s5, v22
	v_mad_u64_u32 v[22:23], s[10:11], s4, v22, 0
	v_mul_lo_u32 v34, s4, v32
	v_mul_lo_u32 v35, s5, v2
	v_mad_u64_u32 v[32:33], s[4:5], s4, v2, 0
	v_add3_u32 v7, v7, v8, v9
	v_add3_u32 v15, v15, v16, v17
	v_add3_u32 v23, v23, v24, v25
	v_add3_u32 v33, v33, v34, v35
	v_lshl_add_u64 v[6:7], v[6:7], 2, s[0:1]
	v_lshl_add_u64 v[12:13], v[12:13], 2, s[0:1]
	v_lshl_add_u64 v[14:15], v[14:15], 2, s[0:1]
	v_lshl_add_u64 v[20:21], v[20:21], 2, s[0:1]
	v_lshl_add_u64 v[22:23], v[22:23], 2, s[0:1]
	v_lshl_add_u64 v[30:31], v[30:31], 2, s[0:1]
	v_lshl_add_u64 v[32:33], v[32:33], 2, s[0:1]
	v_lshl_add_u64 v[8:9], v[6:7], 0, v[28:29]
	v_lshl_add_u64 v[12:13], v[12:13], 0, v[28:29]
	v_lshl_add_u64 v[16:17], v[14:15], 0, v[28:29]
	v_lshl_add_u64 v[20:21], v[20:21], 0, v[28:29]
	v_lshl_add_u64 v[24:25], v[22:23], 0, v[28:29]
	v_lshl_add_u64 v[30:31], v[30:31], 0, v[28:29]
	v_lshl_add_u64 v[32:33], v[32:33], 0, v[28:29]
	global_load_dwordx4 v[4:7], v[4:5], off nt
	s_nop 0
	global_load_dwordx4 v[8:11], v[8:9], off nt
	s_nop 0
	global_load_dwordx4 v[12:15], v[12:13], off nt
	s_nop 0
	global_load_dwordx4 v[16:19], v[16:17], off nt
	s_nop 0
	global_load_dwordx4 v[20:23], v[20:21], off nt
	s_nop 0
	global_load_dwordx4 v[24:27], v[24:25], off nt
	s_nop 0
	global_load_dwordx4 v[28:31], v[30:31], off nt
	s_nop 0
	global_load_dwordx4 v[32:35], v[32:33], off nt
	v_lshlrev_b32_e32 v2, 4, v0
	s_movk_i32 s0, 0x410
	v_and_b32_e32 v2, 0x3f0, v2
	v_mul_lo_u32 v1, v1, s0
	v_add3_u32 v1, 0, v2, v1
	s_waitcnt vmcnt(7)
	ds_write_b128 v1, v[4:7]
	s_waitcnt vmcnt(6)
	ds_write_b128 v1, v[8:11] offset:8320
	s_waitcnt vmcnt(5)
	ds_write_b128 v1, v[12:15] offset:16640
	s_waitcnt vmcnt(4)
	ds_write_b128 v1, v[16:19] offset:24960
	s_waitcnt vmcnt(3)
	ds_write_b128 v1, v[20:23] offset:33280
	s_waitcnt vmcnt(2)
	ds_write_b128 v1, v[24:27] offset:41600
	s_waitcnt vmcnt(1)
	ds_write_b128 v1, v[28:31] offset:49920
	s_waitcnt vmcnt(0)
	ds_write_b128 v1, v[32:35] offset:58240
	v_ashrrev_i32_e32 v1, 1, v0
	v_lshlrev_b32_e32 v0, 5, v0
	v_and_b32_e32 v4, 32, v0
	v_lshlrev_b32_e32 v5, 2, v1
	v_lshlrev_b32_e32 v2, 1, v4
	v_mul_u32_u24_e32 v4, 0x410, v4
	v_add3_u32 v8, 0, v5, v4
	s_waitcnt lgkmcnt(0)
	s_barrier
	v_add_u32_e32 v0, s8, v1
	ds_read_b32 v4, v8
	ds_read_b32 v5, v8 offset:1040
	ds_read_b32 v6, v8 offset:2080
	ds_read_b32 v7, v8 offset:3120
	ds_read_b32 v9, v8 offset:4160
	ds_read_b32 v10, v8 offset:5200
	ds_read_b32 v11, v8 offset:6240
	ds_read_b32 v12, v8 offset:7280
	v_ashrrev_i32_e32 v1, 31, v0
	v_lshlrev_b64 v[0:1], 12, v[0:1]
	v_lshl_add_u64 v[0:1], s[6:7], 0, v[0:1]
	v_lshl_add_u64 v[0:1], v[0:1], 0, s[18:19]
	v_lshl_add_u64 v[0:1], v[0:1], 0, v[2:3]
	s_waitcnt lgkmcnt(6)
	v_cvt_pk_bf16_f32 v4, v4, v5
	s_waitcnt lgkmcnt(4)
	v_cvt_pk_bf16_f32 v5, v6, v7
	s_waitcnt lgkmcnt(2)
	v_cvt_pk_bf16_f32 v6, v9, v10
	s_waitcnt lgkmcnt(0)
	v_cvt_pk_bf16_f32 v7, v11, v12
	ds_read_b32 v2, v8 offset:8320
	ds_read_b32 v9, v8 offset:9360
	ds_read_b32 v10, v8 offset:10400
	ds_read_b32 v11, v8 offset:11440
	ds_read_b32 v12, v8 offset:12480
	ds_read_b32 v13, v8 offset:13520
	ds_read_b32 v14, v8 offset:14560
	ds_read_b32 v15, v8 offset:15600
	global_store_dwordx4 v[0:1], v[4:7], off
	s_mov_b64 s[0:1], 0
	s_waitcnt lgkmcnt(6)
	v_cvt_pk_bf16_f32 v4, v2, v9
	s_waitcnt lgkmcnt(4)
	v_cvt_pk_bf16_f32 v5, v10, v11
	s_waitcnt lgkmcnt(2)
	v_cvt_pk_bf16_f32 v6, v12, v13
	s_waitcnt lgkmcnt(0)
	v_cvt_pk_bf16_f32 v7, v14, v15
	ds_read_b32 v2, v8 offset:16640
	ds_read_b32 v9, v8 offset:17680
	ds_read_b32 v10, v8 offset:18720
	ds_read_b32 v11, v8 offset:19760
	ds_read_b32 v12, v8 offset:20800
	ds_read_b32 v13, v8 offset:21840
	ds_read_b32 v14, v8 offset:22880
	ds_read_b32 v15, v8 offset:23920
	global_store_dwordx4 v[0:1], v[4:7], off offset:16
	s_waitcnt lgkmcnt(6)
	s_nop 0
	v_cvt_pk_bf16_f32 v4, v2, v9
	s_waitcnt lgkmcnt(4)
	v_cvt_pk_bf16_f32 v5, v10, v11
	s_waitcnt lgkmcnt(2)
	v_cvt_pk_bf16_f32 v6, v12, v13
	s_waitcnt lgkmcnt(0)
	v_cvt_pk_bf16_f32 v7, v14, v15
	ds_read_b32 v2, v8 offset:24960
	ds_read_b32 v9, v8 offset:26000
	ds_read_b32 v10, v8 offset:27040
	ds_read_b32 v11, v8 offset:28080
	ds_read_b32 v12, v8 offset:29120
	ds_read_b32 v13, v8 offset:30160
	ds_read_b32 v14, v8 offset:31200
	ds_read_b32 v8, v8 offset:32240
	global_store_dwordx4 v[0:1], v[4:7], off offset:32
	s_waitcnt lgkmcnt(6)
	s_nop 0
	v_cvt_pk_bf16_f32 v4, v2, v9
	s_waitcnt lgkmcnt(4)
	v_cvt_pk_bf16_f32 v5, v10, v11
	s_waitcnt lgkmcnt(2)
	v_cvt_pk_bf16_f32 v6, v12, v13
	s_waitcnt lgkmcnt(0)
	v_cvt_pk_bf16_f32 v7, v14, v8
	global_store_dwordx4 v[0:1], v[4:7], off offset:48
	s_barrier
